# LRU tile loop and LN0/LN1 row loops: waits moved ahead of the stores so stores are no longer drained by in-order vmcnt waits; LN scale/shift vectors loaded up front
# speedup vs baseline: 1.0543x; 1.0160x over previous
; __device__ __forceinline__ void phase_ln0(const Params& p, int g, int gw, int NGW, int lane) {
;     const float* mod = (const float*)(p.ws + OFF_MOD); bf16_t* h0 = (bf16_t*)(p.ws + OFF_H0);
;     f32x4 nx[4];
;     if (gw < RG) { const float* src = ln0_src(p, g, gw);
; #pragma unroll
;         for (int j = 0; j < 4; ++j) nx[j] = *(const f32x4*)(src + 4 * lane + 256 * j); }
;     for (int row = gw; row < RG; row += NGW) {
;         const int mrow = (row < CGR) ? 32 : g * BG + (row - CGR) / SEQ;
.LBB0_239:
	s_cmp_gt_u32 s57, 11
	s_cbranch_scc1 .LBB0_248
	s_cmp_gt_i32 s26, 0x8fff
	s_cbranch_scc1 .LBB0_248
	s_add_i32 s66, s38, 1
	s_waitcnt lgkmcnt(0)
	s_lshl_b32 s10, s66, 4
	s_add_i32 s11, s26, 0xfffff000
	s_ashr_i32 s27, s26, 31
	s_cmpk_lt_i32 s26, 0x1000
	s_cselect_b32 s2, 24, 27
	s_cselect_b32 s4, s61, s45
	s_cselect_b32 s5, s60, s44
	s_cselect_b32 s1, s27, 0
	s_cselect_b32 s0, s26, s11
	s_lshl_b64 s[2:3], s[66:67], s2
	s_add_u32 s2, s5, s2
	s_addc_u32 s3, s4, s3
	s_lshl_b64 s[0:1], s[0:1], 12
	s_add_u32 s0, s2, s0
	s_addc_u32 s1, s3, s1
	v_lshlrev_b32_e32 v39, 2, v86
	global_load_dwordx4 v[28:31], v39, s[0:1]
	global_load_dwordx4 v[8:11], v39, s[0:1] offset:1024
	global_load_dwordx4 v[4:7], v39, s[0:1] offset:2048
	global_load_dwordx4 v[0:3], v39, s[0:1] offset:3072
	s_lshl_b64 s[0:1], s[26:27], 11
	s_add_u32 s0, s94, s0
	v_lshlrev_b32_e32 v192, 3, v244
	s_addc_u32 s1, s95, s1
	v_or_b32_e32 v12, 0x100, v86
	v_or_b32_e32 v14, 0x200, v86
	v_or_b32_e32 v16, 0x300, v86
	v_lshl_add_u64 v[18:19], s[0:1], 0, v[192:193]
	s_mov_b64 s[0:1], 0x3100000
	v_xor_b32_e32 v40, 4, v86
	v_xor_b32_e32 v41, 8, v86
	v_xor_b32_e32 v42, 16, v86
	v_xor_b32_e32 v43, 32, v86
	v_xor_b32_e32 v44, 64, v86
	v_xor_b32_e32 v45, 0x80, v86
	v_lshl_add_u64 v[36:37], v[18:19], 0, s[0:1]
	v_lshlrev_b32_e32 v46, 2, v12
	v_lshlrev_b32_e32 v47, 2, v14
	v_lshlrev_b32_e32 v48, 2, v16
	s_waitcnt vmcnt(0)
	s_branch .LBB0_243
; __device__ __forceinline__ unsigned cvt_pk_bf16(float lo, float hi) { unsigned r; asm volatile("s_nop 0\n\tv_cvt_pk_bf16_f32 %0, %1, %2\n\ts_nop 1" : "=v"(r) : "v"(lo), "v"(hi)); return r; }
; __device__ __forceinline__ void phase_ln0(const Params& p, int g, int gw, int NGW, int lane) {
;     ...
;         const float* sh = mod + (size_t)mrow * MODW; const float* sc = sh + DM;
;         f32x4 v[4]; float s = 0.f;
; #pragma unroll
;         for (int j = 0; j < 4; ++j) { v[j] = nx[j]; s += (v[j].x + v[j].y) + (v[j].z + v[j].w); }
;         if (row + NGW < RG) { const float* src = ln0_src(p, g, row + NGW);
; #pragma unroll
;             for (int j = 0; j < 4; ++j) nx[j] = *(const f32x4*)(src + 4 * lane + 256 * j); }
;         const float mean = wave_sum(s, lane) * (1.f / DM); float s2 = 0.f;
; #pragma unroll
;         for (int j = 0; j < 4; ++j) { v[j] = v[j] - mean; s2 += (v[j].x * v[j].x + v[j].y * v[j].y) + (v[j].z * v[j].z + v[j].w * v[j].w); }
;         const float rstd = __builtin_amdgcn_rsqf(wave_sum(s2, lane) * (1.f / DM) + 1e-6f);
; #pragma unroll
;         for (int j = 0; j < 4; ++j) { const int col = 4 * lane + 256 * j; const f32x4 a = *(const f32x4*)(sc + col), b = *(const f32x4*)(sh + col);
;             const f32x4 o = v[j] * rstd * (a + 1.f) + b; u32x2 w; w.x = cvt_pk_bf16(o.x, o.y); w.y = cvt_pk_bf16(o.z, o.w);
;             *(u32x2*)(h0 + (size_t)row * DM + col) = w; }
.LBB0_242:
	v_add_f32_e32 v32, v28, v29
	v_add_f32_e32 v33, v30, v31
	v_add_f32_e32 v32, v32, v33
	v_add_f32_e32 v33, v8, v9
	v_add_f32_e32 v34, v10, v11
	v_add_f32_e32 v32, 0, v32
	v_add_f32_e32 v33, v33, v34
	v_add_f32_e32 v32, v33, v32
	v_add_f32_e32 v33, v4, v5
	v_add_f32_e32 v34, v6, v7
	v_add_f32_e32 v33, v33, v34
	v_add_f32_e32 v32, v33, v32
	v_add_f32_e32 v33, v0, v1
	v_add_f32_e32 v34, v2, v3
	v_add_f32_e32 v33, v33, v34
	v_add_f32_e32 v32, v33, v32
	ds_bpermute_b32 v33, v40, v32
	s_lshl_b64 s[2:3], s[2:3], 2
	s_add_u32 s2, s94, s2
	s_addc_u32 s3, s95, s3
	s_add_u32 s4, s2, 0x1000
	s_waitcnt lgkmcnt(0)
	v_add_f32_e32 v32, v32, v33
	ds_bpermute_b32 v33, v41, v32
	s_addc_u32 s5, s3, 0
	s_andn2_b64 vcc, exec, s[0:1]
	s_waitcnt lgkmcnt(0)
	v_add_f32_e32 v32, v32, v33
	ds_bpermute_b32 v33, v42, v32
	s_waitcnt lgkmcnt(0)
	v_add_f32_e32 v32, v32, v33
	ds_bpermute_b32 v33, v43, v32
	s_waitcnt lgkmcnt(0)
	v_add_f32_e32 v32, v32, v33
	ds_bpermute_b32 v33, v44, v32
	s_waitcnt lgkmcnt(0)
	v_add_f32_e32 v32, v32, v33
	ds_bpermute_b32 v33, v45, v32
	s_waitcnt lgkmcnt(0)
	v_add_f32_e32 v38, v32, v33
	v_fmac_f32_e32 v29, 0xba800000, v38
	v_fmac_f32_e32 v28, 0xba800000, v38
	v_fmac_f32_e32 v31, 0xba800000, v38
	v_fmac_f32_e32 v30, 0xba800000, v38
	v_pk_mul_f32 v[32:33], v[30:31], v[30:31]
	v_pk_mul_f32 v[34:35], v[28:29], v[28:29]
	v_fmac_f32_e32 v9, 0xba800000, v38
	v_pk_mov_b32 v[50:51], v[34:35], v[32:33] op_sel:[1,0]
	v_mov_b32_e32 v35, v33
	v_pk_add_f32 v[32:33], v[50:51], v[34:35]
	v_fmac_f32_e32 v8, 0xba800000, v38
	v_fmac_f32_e32 v11, 0xba800000, v38
	v_fmac_f32_e32 v10, 0xba800000, v38
	v_pk_add_f32 v[32:33], v[32:33], v[32:33] op_sel_hi:[0,1]
	v_pk_mul_f32 v[34:35], v[10:11], v[10:11]
	v_pk_mul_f32 v[50:51], v[8:9], v[8:9]
	v_fmac_f32_e32 v4, 0xba800000, v38
	v_pk_mov_b32 v[52:53], v[50:51], v[34:35] op_sel:[1,0]
	v_mov_b32_e32 v51, v35
	v_fmac_f32_e32 v5, 0xba800000, v38
	v_fmac_f32_e32 v6, 0xba800000, v38
	v_mul_f32_e32 v32, v4, v4
	v_pk_add_f32 v[34:35], v[52:53], v[50:51]
	v_fmac_f32_e32 v7, 0xba800000, v38
	v_pk_fma_f32 v[50:51], v[4:5], v[4:5], v[32:33] op_sel_hi:[1,1,0]
	v_mul_f32_e32 v32, v6, v6
	v_pk_add_f32 v[34:35], v[34:35], v[34:35] op_sel_hi:[0,1]
	v_pk_fma_f32 v[52:53], v[6:7], v[6:7], v[32:33] op_sel_hi:[1,1,0]
	v_fmac_f32_e32 v3, 0xba800000, v38
	v_fmac_f32_e32 v2, 0xba800000, v38
	v_fmac_f32_e32 v1, 0xba800000, v38
	v_fmac_f32_e32 v0, 0xba800000, v38
	v_mul_f32_e32 v50, v0, v0
	v_mul_f32_e32 v52, v1, v1
	v_mul_f32_e32 v32, v2, v2
	v_mul_f32_e32 v34, v3, v3
	v_pk_add_f32 v[50:51], v[50:51], v[52:53]
	v_pk_add_f32 v[32:33], v[32:33], v[34:35]
	s_nop 0
	v_pk_add_f32 v[32:33], v[50:51], v[32:33]
	s_nop 0
	v_add_f32_e32 v32, v32, v33
	ds_bpermute_b32 v33, v40, v32
	s_waitcnt lgkmcnt(0)
	v_add_f32_e32 v32, v32, v33
	ds_bpermute_b32 v33, v41, v32
	s_waitcnt lgkmcnt(0)
	v_add_f32_e32 v32, v32, v33
	ds_bpermute_b32 v33, v42, v32
	s_waitcnt lgkmcnt(0)
	v_add_f32_e32 v32, v32, v33
	ds_bpermute_b32 v33, v43, v32
	s_waitcnt lgkmcnt(0)
	v_add_f32_e32 v32, v32, v33
	ds_bpermute_b32 v33, v44, v32
	s_waitcnt lgkmcnt(0)
	v_add_f32_e32 v32, v32, v33
	ds_bpermute_b32 v33, v45, v32
	s_waitcnt lgkmcnt(0)
	v_add_f32_e32 v32, v32, v33
	v_fmamk_f32 v32, v32, 0x3a800000, v238
	v_rsq_f32_e32 v38, v32
	global_load_dwordx4 v[32:35], v39, s[4:5]
	global_load_dwordx4 v[50:53], v39, s[2:3]
	global_load_dwordx4 v[100:103], v46, s[4:5]
	global_load_dwordx4 v[104:107], v39, s[2:3] offset:1024
	global_load_dwordx4 v[108:111], v47, s[4:5]
	global_load_dwordx4 v[112:115], v39, s[2:3] offset:2048
	global_load_dwordx4 v[116:119], v48, s[4:5]
	global_load_dwordx4 v[120:123], v39, s[2:3] offset:3072
	v_pk_mul_f32 v[28:29], v[28:29], v[38:39] op_sel_hi:[1,0]
	v_pk_mul_f32 v[30:31], v[30:31], v[38:39] op_sel_hi:[1,0]
	v_pk_mul_f32 v[8:9], v[8:9], v[38:39] op_sel_hi:[1,0]
	v_pk_mul_f32 v[10:11], v[10:11], v[38:39] op_sel_hi:[1,0]
	v_pk_mul_f32 v[4:5], v[4:5], v[38:39] op_sel_hi:[1,0]
	v_pk_mul_f32 v[6:7], v[6:7], v[38:39] op_sel_hi:[1,0]
	v_pk_mul_f32 v[0:1], v[0:1], v[38:39] op_sel_hi:[1,0]
	v_pk_mul_f32 v[2:3], v[2:3], v[38:39] op_sel_hi:[1,0]
	s_waitcnt vmcnt(0)
	v_pk_add_f32 v[32:33], v[32:33], 1.0 op_sel_hi:[1,0]
	v_pk_add_f32 v[34:35], v[34:35], 1.0 op_sel_hi:[1,0]
	v_pk_fma_f32 v[28:29], v[32:33], v[28:29], v[50:51]
	v_pk_fma_f32 v[30:31], v[34:35], v[30:31], v[52:53]
	v_cvt_pk_bf16_f32 v28, v28, v29
	s_nop 0
	v_cvt_pk_bf16_f32 v29, v30, v31
	global_store_dwordx2 v[36:37], v[28:29], off
	s_nop 0
	v_pk_add_f32 v[28:29], v[100:101], 1.0 op_sel_hi:[1,0]
	v_pk_add_f32 v[30:31], v[102:103], 1.0 op_sel_hi:[1,0]
	v_pk_fma_f32 v[8:9], v[28:29], v[8:9], v[104:105]
	v_pk_fma_f32 v[10:11], v[30:31], v[10:11], v[106:107]
	v_cvt_pk_bf16_f32 v8, v8, v9
	s_nop 0
	v_cvt_pk_bf16_f32 v9, v10, v11
	global_store_dwordx2 v[36:37], v[8:9], off offset:512
	s_nop 0
	v_pk_add_f32 v[8:9], v[108:109], 1.0 op_sel_hi:[1,0]
	v_pk_add_f32 v[10:11], v[110:111], 1.0 op_sel_hi:[1,0]
	v_pk_fma_f32 v[4:5], v[8:9], v[4:5], v[112:113]
	v_pk_fma_f32 v[6:7], v[10:11], v[6:7], v[114:115]
	v_cvt_pk_bf16_f32 v4, v4, v5
	v_mov_b32_e32 v28, v16
	v_cvt_pk_bf16_f32 v5, v6, v7
	global_store_dwordx2 v[36:37], v[4:5], off offset:1024
	s_nop 0
	v_readlane_b32 s2, v255, 2
	v_readlane_b32 s3, v255, 3
	v_mov_b32_e32 v29, v17
	v_mov_b32_e32 v30, v18
	v_mov_b32_e32 v31, v19
	v_pk_add_f32 v[4:5], v[116:117], 1.0 op_sel_hi:[1,0]
	v_pk_add_f32 v[6:7], v[118:119], 1.0 op_sel_hi:[1,0]
	v_pk_fma_f32 v[0:1], v[4:5], v[0:1], v[120:121]
	v_pk_fma_f32 v[2:3], v[6:7], v[2:3], v[122:123]
	v_cvt_pk_bf16_f32 v0, v0, v1
	v_mov_b32_e32 v8, v20
	v_cvt_pk_bf16_f32 v1, v2, v3
	global_store_dwordx2 v[36:37], v[0:1], off offset:1536
	v_lshl_add_u64 v[36:37], v[36:37], 0, s[2:3]
	v_mov_b32_e32 v9, v21
	v_mov_b32_e32 v10, v22
	v_mov_b32_e32 v11, v23
	v_mov_b32_e32 v4, v24
	v_mov_b32_e32 v5, v25
	v_mov_b32_e32 v6, v26
	v_mov_b32_e32 v7, v27
	v_mov_b32_e32 v0, v12
	v_mov_b32_e32 v1, v13
	v_mov_b32_e32 v2, v14
	v_mov_b32_e32 v3, v15
	s_cbranch_vccz .LBB0_247

; __device__ __forceinline__ void phase_ln0(const Params& p, int g, int gw, int NGW, int lane) {
;     ...
;     for (int row = gw; row < RG; row += NGW) {
;         const int mrow = (row < CGR) ? 32 : g * BG + (row - CGR) / SEQ;
;         const float* sh = mod + (size_t)mrow * MODW; const float* sc = sh + DM;
;         f32x4 v[4]; float s = 0.f;
; #pragma unroll
;         for (int j = 0; j < 4; ++j) { v[j] = nx[j]; s += (v[j].x + v[j].y) + (v[j].z + v[j].w); }
;         if (row + NGW < RG) { const float* src = ln0_src(p, g, row + NGW);
; #pragma unroll
;             for (int j = 0; j < 4; ++j) nx[j] = *(const f32x4*)(src + 4 * lane + 256 * j); }
.LBB0_245:
	v_readlane_b32 s0, v255, 12
	s_add_i32 s11, s0, s11
	s_add_i32 s4, s11, 0x1000
	v_readlane_b32 s1, v255, 13
	s_cmp_gt_i32 s4, 0x8fff
	s_cselect_b64 s[0:1], -1, 0
	s_and_b64 vcc, exec, s[0:1]
	v_mov_b32_e32 v16, v28
	v_mov_b32_e32 v17, v29
	v_mov_b32_e32 v18, v30
	v_mov_b32_e32 v19, v31
	v_mov_b32_e32 v20, v8
	v_mov_b32_e32 v21, v9
	v_mov_b32_e32 v22, v10
	v_mov_b32_e32 v23, v11
	v_mov_b32_e32 v24, v4
	v_mov_b32_e32 v25, v5
	v_mov_b32_e32 v26, v6
	v_mov_b32_e32 v27, v7
	v_mov_b32_e32 v12, v0
	v_mov_b32_e32 v13, v1
	v_mov_b32_e32 v14, v2
	v_mov_b32_e32 v15, v3
	s_cbranch_vccnz .LBB0_242
	s_ashr_i32 s5, s4, 31
	s_cmpk_lt_i32 s4, 0x1000
	s_cselect_b32 s12, 24, 27
	s_cselect_b32 s14, s61, s45
	s_cselect_b32 s15, s60, s44
	s_cselect_b32 s5, s5, 0
	s_cselect_b32 s4, s4, s11
	s_lshl_b64 s[12:13], s[66:67], s12
	s_add_u32 s12, s15, s12
	s_addc_u32 s13, s14, s13
	s_lshl_b64 s[4:5], s[4:5], 12
	s_add_u32 s4, s12, s4
	s_addc_u32 s5, s13, s5
	global_load_dwordx4 v[16:19], v39, s[4:5]
	global_load_dwordx4 v[20:23], v39, s[4:5] offset:1024
	global_load_dwordx4 v[24:27], v39, s[4:5] offset:2048
	global_load_dwordx4 v[12:15], v39, s[4:5] offset:3072
	s_branch .LBB0_242

; __device__ __forceinline__ float bflo(unsigned w) { return __uint_as_float(w << 16); }
; __device__ __forceinline__ float bfhi(unsigned w) { return __uint_as_float(w & 0xffff0000u); }
; __device__ __forceinline__ void phase_ln1(const Params& p, int g, int gw, int NGW, int lane) {
;     ...
;     f32x4 gaH[4], beH[4];
; #pragma unroll
;     for (int j = 0; j < 4; ++j) { gaH[j] = *(const f32x4*)(p.ln1_g + 4 * lane + 256 * j); beH[j] = *(const f32x4*)(p.ln1_b + 4 * lane + 256 * j); }
;     f32x4 nx[4]; u32x2 nb[4];
;     if (gw < TG) {
; #pragma unroll
;         for (int j = 0; j < 4; ++j) { nx[j] = *(const f32x4*)(xbase + (size_t)gw * DM + 4 * lane + 256 * j); nb[j] = *(const u32x2*)(brbase + (size_t)gw * DM + 4 * lane + 256 * j); } }
;     for (int row = gw; row < TG; row += NGW) {
;         const int b = g * BG + row / SEQ; const float* sh = mod + (size_t)b * MODW + 3 * DM; const float* sc = sh + DM;
;         float* xr = x1 + (size_t)row * DM;
;         f32x4 v[4]; float s = 0.f;
; #pragma unroll
;         for (int j = 0; j < 4; ++j) { const u32x2 bw = nb[j];
;             v[j] = nx[j] * ALPHA + (f32x4){bflo(bw.x), bfhi(bw.x), bflo(bw.y), bfhi(bw.y)}; s += (v[j].x + v[j].y) + (v[j].z + v[j].w); }
;         if (row + NGW < TG) { const size_t nr = (size_t)(row + NGW) * DM;
; #pragma unroll
;             for (int j = 0; j < 4; ++j) { nx[j] = *(const f32x4*)(xbase + nr + 4 * lane + 256 * j); nb[j] = *(const u32x2*)(brbase + nr + 4 * lane + 256 * j); } }
;         float mean = wave_sum(s, lane) * (1.f / DM); float s2 = 0.f;
; #pragma unroll
;         for (int j = 0; j < 4; ++j) { v[j] = v[j] - mean; s2 += (v[j].x * v[j].x + v[j].y * v[j].y) + (v[j].z * v[j].z + v[j].w * v[j].w); }
.LBB0_301:
	s_andn2_b64 vcc, exec, s[0:1]
	s_cbranch_vccnz .LBB0_330
	s_cmp_gt_i32 s79, 6
	s_mov_b64 s[0:1], -1
	s_cbranch_scc0 .LBB0_309
	s_cmpk_gt_i32 s26, 0x7fff
	s_cbranch_scc1 .LBB0_308
	v_lshlrev_b32_e32 v192, 4, v244
	s_waitcnt lgkmcnt(0)
	global_load_dwordx4 v[0:3], v192, s[16:17]
	global_load_dwordx4 v[4:7], v192, s[18:19]
	global_load_dwordx4 v[8:11], v192, s[16:17] offset:1024
	global_load_dwordx4 v[12:15], v192, s[18:19] offset:1024
	global_load_dwordx4 v[16:19], v192, s[16:17] offset:2048
	global_load_dwordx4 v[20:23], v192, s[18:19] offset:2048
	global_load_dwordx4 v[24:27], v192, s[16:17] offset:3072
	global_load_dwordx4 v[28:31], v192, s[18:19] offset:3072
	s_add_u32 s0, s94, 0x17900000
	s_addc_u32 s1, s95, 0
	s_add_u32 s2, s44, s20
	s_addc_u32 s3, s45, s21
	s_ashr_i32 s27, s26, 31
	s_lshl_b64 s[6:7], s[26:27], 12
	s_add_u32 s4, s2, s6
	s_addc_u32 s5, s3, s7
	s_lshl_b64 s[8:9], s[26:27], 11
	s_add_u32 s10, s0, s8
	s_addc_u32 s11, s1, s9
	v_lshlrev_b32_e32 v32, 3, v244
	global_load_dwordx2 v[86:87], v32, s[10:11]
	global_load_dwordx2 v[84:85], v32, s[10:11] offset:512
	global_load_dwordx2 v[82:83], v32, s[10:11] offset:1024
	global_load_dwordx2 v[80:81], v32, s[10:11] offset:1536
	global_load_dwordx4 v[60:63], v192, s[4:5]
	global_load_dwordx4 v[56:59], v192, s[4:5] offset:1024
	global_load_dwordx4 v[52:55], v192, s[4:5] offset:2048
	global_load_dwordx4 v[48:51], v192, s[4:5] offset:3072
	v_lshlrev_b32_e32 v34, 2, v244
	v_mov_b32_e32 v33, v193
	v_or_b32_e32 v36, 0x100, v34
	v_or_b32_e32 v38, 0x200, v34
	v_or_b32_e32 v40, 0x300, v34
	s_mov_b32 s4, s26
	v_xor_b32_e32 v88, 4, v34
	v_xor_b32_e32 v89, 8, v34
	v_xor_b32_e32 v90, 16, v34
	v_xor_b32_e32 v91, 32, v34
	v_xor_b32_e32 v92, 64, v34
	v_xor_b32_e32 v93, 0x80, v34
	v_lshlrev_b32_e32 v94, 2, v34
	v_lshl_add_u64 v[64:65], s[0:1], 0, v[32:33]
	v_lshlrev_b32_e32 v95, 2, v36
	v_lshlrev_b32_e32 v96, 2, v38
	v_lshlrev_b32_e32 v97, 2, v40
	v_lshl_add_u64 v[66:67], s[2:3], 0, v[192:193]
	v_lshl_or_b32 v68, v244, 4, s6
	v_mov_b32_e32 v69, s7
	v_lshl_or_b32 v70, v244, 3, s8
	v_mov_b32_e32 v71, s9
	s_waitcnt vmcnt(0)
	v_mov_b64_e32 v[78:79], v[86:87]
	s_waitcnt vmcnt(6)
	v_mov_b64_e32 v[76:77], v[84:85]
	s_waitcnt vmcnt(5)
	v_mov_b64_e32 v[74:75], v[82:83]
	s_waitcnt vmcnt(4)
	v_mov_b64_e32 v[72:73], v[80:81]
	s_waitcnt vmcnt(0)
	s_branch .LBB0_306
.LBB0_305:
	v_lshlrev_b32_e32 v98, 16, v86
	v_and_b32_e32 v99, 0xffff0000, v86
	v_lshlrev_b32_e32 v86, 16, v87
	v_and_b32_e32 v87, 0xffff0000, v87
	v_pk_fma_f32 v[62:63], v[62:63], s[70:71], v[86:87] op_sel_hi:[1,0,1]
	v_pk_fma_f32 v[60:61], v[60:61], s[70:71], v[98:99] op_sel_hi:[1,0,1]
	v_add_f32_e32 v87, v62, v63
	v_add_f32_e32 v86, v60, v61
	v_add_f32_e32 v86, v86, v87
	v_add_f32_e32 v98, 0, v86
	v_lshlrev_b32_e32 v86, 16, v84
	v_and_b32_e32 v87, 0xffff0000, v84
	v_lshlrev_b32_e32 v84, 16, v85
	v_and_b32_e32 v85, 0xffff0000, v85
	v_pk_fma_f32 v[58:59], v[58:59], s[70:71], v[84:85] op_sel_hi:[1,0,1]
	v_pk_fma_f32 v[56:57], v[56:57], s[70:71], v[86:87] op_sel_hi:[1,0,1]
	v_add_f32_e32 v85, v58, v59
	v_add_f32_e32 v84, v56, v57
	v_add_f32_e32 v84, v84, v85
	v_add_f32_e32 v86, v84, v98
	v_lshlrev_b32_e32 v84, 16, v82
	v_and_b32_e32 v85, 0xffff0000, v82
	v_lshlrev_b32_e32 v82, 16, v83
	v_and_b32_e32 v83, 0xffff0000, v83
	v_pk_fma_f32 v[82:83], v[54:55], s[70:71], v[82:83] op_sel_hi:[1,0,1]
	v_pk_fma_f32 v[84:85], v[52:53], s[70:71], v[84:85] op_sel_hi:[1,0,1]
	v_add_f32_e32 v53, v82, v83
	v_add_f32_e32 v52, v84, v85
	v_add_f32_e32 v52, v52, v53
	v_add_f32_e32 v98, v52, v86
	v_lshlrev_b32_e32 v52, 16, v80
	v_and_b32_e32 v53, 0xffff0000, v80
	v_lshlrev_b32_e32 v54, 16, v81
	v_and_b32_e32 v55, 0xffff0000, v81
	v_pk_fma_f32 v[80:81], v[50:51], s[70:71], v[54:55] op_sel_hi:[1,0,1]
	v_pk_fma_f32 v[86:87], v[48:49], s[70:71], v[52:53] op_sel_hi:[1,0,1]
	v_add_f32_e32 v49, v80, v81
	v_add_f32_e32 v48, v86, v87
	v_add_f32_e32 v48, v48, v49
	v_add_f32_e32 v48, v48, v98
	ds_bpermute_b32 v49, v88, v48
	s_ashr_i32 s1, s4, 31
	s_lshr_b32 s1, s1, 21
	s_add_i32 s1, s4, s1
	s_ashr_i32 s1, s1, 11
	s_waitcnt lgkmcnt(0)
	v_add_f32_e32 v48, v48, v49
	ds_bpermute_b32 v49, v89, v48
	s_add_i32 s1, s1, s76
	s_mul_hi_i32 s4, s1, 0x6000
	s_mulk_i32 s1, 0x6000
	s_add_u32 s1, s94, s1
	s_waitcnt lgkmcnt(0)
	v_add_f32_e32 v48, v48, v49
	ds_bpermute_b32 v49, v90, v48
	s_addc_u32 s7, s95, s4
	s_add_u32 s4, s1, 0x3000
	s_addc_u32 s5, s7, 0
	s_add_u32 s6, s1, 0x4000
	s_waitcnt lgkmcnt(0)
	v_add_f32_e32 v48, v48, v49
	ds_bpermute_b32 v49, v91, v48
	s_addc_u32 s7, s7, 0
	s_mov_b32 s1, 0xf900000
	s_waitcnt lgkmcnt(0)
	v_add_f32_e32 v48, v48, v49
	ds_bpermute_b32 v49, v92, v48
	s_waitcnt lgkmcnt(0)
	v_add_f32_e32 v48, v48, v49
	ds_bpermute_b32 v49, v93, v48
	s_waitcnt lgkmcnt(0)
	v_add_f32_e32 v98, v48, v49
	v_fmamk_f32 v61, v98, 0xba800000, v61
	v_fmac_f32_e32 v60, 0xba800000, v98
	v_fmamk_f32 v63, v98, 0xba800000, v63
	v_fmac_f32_e32 v62, 0xba800000, v98
	v_pk_mul_f32 v[48:49], v[62:63], v[62:63]
	v_pk_mul_f32 v[50:51], v[60:61], v[60:61]
	v_fmamk_f32 v57, v98, 0xba800000, v57
	v_pk_mov_b32 v[52:53], v[50:51], v[48:49] op_sel:[1,0]
	v_mov_b32_e32 v51, v49
	v_pk_add_f32 v[48:49], v[52:53], v[50:51]
	v_fmac_f32_e32 v56, 0xba800000, v98
	v_fmamk_f32 v59, v98, 0xba800000, v59
	v_fmac_f32_e32 v58, 0xba800000, v98
	v_pk_add_f32 v[48:49], v[48:49], v[48:49] op_sel_hi:[0,1]
	v_pk_mul_f32 v[50:51], v[58:59], v[58:59]
	v_pk_mul_f32 v[52:53], v[56:57], v[56:57]
	v_fmac_f32_e32 v84, 0xba800000, v98
	v_pk_mov_b32 v[54:55], v[52:53], v[50:51] op_sel:[1,0]
	v_mov_b32_e32 v53, v51
	v_fmamk_f32 v85, v98, 0xba800000, v85
	v_fmac_f32_e32 v82, 0xba800000, v98
	v_mul_f32_e32 v48, v84, v84
	v_pk_add_f32 v[50:51], v[54:55], v[52:53]
	v_fmamk_f32 v83, v98, 0xba800000, v83
	v_pk_fma_f32 v[52:53], v[84:85], v[84:85], v[48:49] op_sel_hi:[1,1,0]
	v_mul_f32_e32 v48, v82, v82
	v_pk_add_f32 v[50:51], v[50:51], v[50:51] op_sel_hi:[0,1]
	v_pk_fma_f32 v[54:55], v[82:83], v[82:83], v[48:49] op_sel_hi:[1,1,0]
	v_fmamk_f32 v81, v98, 0xba800000, v81
	v_fmac_f32_e32 v80, 0xba800000, v98
	v_fmamk_f32 v87, v98, 0xba800000, v87
	v_fmac_f32_e32 v86, 0xba800000, v98
	v_mul_f32_e32 v52, v86, v86
	v_mul_f32_e32 v54, v87, v87
	v_mul_f32_e32 v48, v80, v80
	v_mul_f32_e32 v50, v81, v81
	v_pk_add_f32 v[52:53], v[52:53], v[54:55]
	v_pk_add_f32 v[48:49], v[48:49], v[50:51]
	s_nop 0
	v_pk_add_f32 v[48:49], v[52:53], v[48:49]
	v_lshl_add_u64 v[52:53], s[94:95], 0, v[68:69]
	v_add_f32_e32 v48, v48, v49
	ds_bpermute_b32 v49, v88, v48
	v_add_co_u32_e32 v100, vcc, s89, v52
	s_waitcnt lgkmcnt(0)
; __device__ __forceinline__ void phase_ln1(const Params& p, int g, int gw, int NGW, int lane) {
;     ...
;         float rstd = __builtin_amdgcn_rsqf(wave_sum(s2, lane) * (1.f / DM) + 1e-6f);
;         s = 0.f;
; #pragma unroll
;         for (int j = 0; j < 4; ++j) { const int col = 4 * lane + 256 * j; const f32x4 ga = gaH[j], be = beH[j];
;             v[j] = v[j] * rstd * ga + be; *(f32x4*)(xr + col) = v[j]; s += (v[j].x + v[j].y) + (v[j].z + v[j].w); }
;         mean = wave_sum(s, lane) * (1.f / DM); s2 = 0.f;
; #pragma unroll
;         for (int j = 0; j < 4; ++j) { v[j] = v[j] - mean; s2 += (v[j].x * v[j].x + v[j].y * v[j].y) + (v[j].z * v[j].z + v[j].w * v[j].w); }
;         rstd = __builtin_amdgcn_rsqf(wave_sum(s2, lane) * (1.f / DM) + 1e-6f);
; #pragma unroll
;         for (int j = 0; j < 4; ++j) { const int col = 4 * lane + 256 * j; const f32x4 a = *(const f32x4*)(sc + col), bb = *(const f32x4*)(sh + col);
	v_add_f32_e32 v48, v48, v49
	ds_bpermute_b32 v49, v89, v48
	v_addc_co_u32_e32 v101, vcc, 0, v53, vcc
	s_waitcnt lgkmcnt(0)
	v_add_f32_e32 v48, v48, v49
	ds_bpermute_b32 v49, v90, v48
	s_waitcnt lgkmcnt(0)
	v_add_f32_e32 v48, v48, v49
	ds_bpermute_b32 v49, v91, v48
	s_waitcnt lgkmcnt(0)
	v_add_f32_e32 v48, v48, v49
	ds_bpermute_b32 v49, v92, v48
	s_waitcnt lgkmcnt(0)
	v_add_f32_e32 v48, v48, v49
	ds_bpermute_b32 v49, v93, v48
	s_waitcnt lgkmcnt(0)
	v_add_f32_e32 v48, v48, v49
	v_fmamk_f32 v48, v48, 0x3a800000, v238
	v_rsq_f32_e32 v98, v48
	s_nop 0
	v_pk_mul_f32 v[50:51], v[62:63], v[98:99] op_sel_hi:[1,0]
	v_pk_mul_f32 v[48:49], v[60:61], v[98:99] op_sel_hi:[1,0]
	v_pk_fma_f32 v[50:51], v[2:3], v[50:51], v[6:7]
	v_pk_fma_f32 v[48:49], v[0:1], v[48:49], v[4:5]
	v_mov_b32_e32 v55, v51
	v_pk_mov_b32 v[52:53], v[48:49], v[50:51] op_sel:[1,0]
	v_mov_b32_e32 v54, v48
	v_pk_add_f32 v[52:53], v[52:53], v[54:55]
	global_store_dwordx4 v[100:101], v[48:51], off
	v_add_f32_e32 v52, v52, v53
	v_add_f32_e32 v99, 0, v52
	v_pk_mul_f32 v[54:55], v[58:59], v[98:99] op_sel_hi:[1,0]
	v_pk_mul_f32 v[52:53], v[56:57], v[98:99] op_sel_hi:[1,0]
	v_pk_fma_f32 v[54:55], v[10:11], v[54:55], v[14:15]
	v_pk_fma_f32 v[52:53], v[8:9], v[52:53], v[12:13]
	v_mov_b32_e32 v59, v55
	v_pk_mov_b32 v[56:57], v[52:53], v[54:55] op_sel:[1,0]
	v_mov_b32_e32 v58, v52
	v_pk_add_f32 v[56:57], v[56:57], v[58:59]
	v_pk_mul_f32 v[58:59], v[82:83], v[98:99] op_sel_hi:[1,0]
	v_pk_add_f32 v[102:103], v[56:57], v[56:57] op_sel_hi:[0,1]
	v_pk_mul_f32 v[56:57], v[84:85], v[98:99] op_sel_hi:[1,0]
	v_pk_mul_f32 v[60:61], v[86:87], v[98:99] op_sel_hi:[1,0]
	v_pk_mul_f32 v[62:63], v[80:81], v[98:99] op_sel_hi:[1,0]
	v_pk_fma_f32 v[56:57], v[16:17], v[56:57], v[20:21]
	v_pk_fma_f32 v[58:59], v[18:19], v[58:59], v[22:23]
	v_pk_fma_f32 v[62:63], v[26:27], v[62:63], v[30:31]
	v_pk_fma_f32 v[60:61], v[24:25], v[60:61], v[28:29]
	v_add_f32_e32 v83, v56, v57
	v_add_f32_e32 v85, v58, v59
	v_mov_b32_e32 v82, v60
	v_mov_b32_e32 v84, v61
	v_mov_b32_e32 v102, v62
	v_mov_b32_e32 v98, v63
	v_pk_add_f32 v[80:81], v[82:83], v[84:85]
	v_pk_add_f32 v[82:83], v[102:103], v[98:99]
	global_store_dwordx4 v[100:101], v[52:55], off offset:1024
	v_pk_add_f32 v[80:81], v[80:81], v[82:83]
	global_store_dwordx4 v[100:101], v[56:59], off offset:2048
	v_add_f32_e32 v80, v80, v81
	ds_bpermute_b32 v81, v88, v80
	global_store_dwordx4 v[100:101], v[60:63], off offset:3072
	s_waitcnt lgkmcnt(0)
	v_add_f32_e32 v80, v80, v81
	ds_bpermute_b32 v81, v89, v80
	s_waitcnt lgkmcnt(0)
	v_add_f32_e32 v80, v80, v81
	ds_bpermute_b32 v81, v90, v80
	s_waitcnt lgkmcnt(0)
	v_add_f32_e32 v80, v80, v81
	ds_bpermute_b32 v81, v91, v80
	s_waitcnt lgkmcnt(0)
	v_add_f32_e32 v80, v80, v81
	ds_bpermute_b32 v81, v92, v80
	s_waitcnt lgkmcnt(0)
	v_add_f32_e32 v80, v80, v81
	ds_bpermute_b32 v81, v93, v80
	s_waitcnt lgkmcnt(0)
	v_add_f32_e32 v98, v80, v81
	v_fmamk_f32 v49, v98, 0xba800000, v49
	v_fmac_f32_e32 v48, 0xba800000, v98
	v_fmamk_f32 v51, v98, 0xba800000, v51
	v_fmac_f32_e32 v50, 0xba800000, v98
	v_pk_mul_f32 v[80:81], v[50:51], v[50:51]
	v_pk_mul_f32 v[82:83], v[48:49], v[48:49]
	v_fmamk_f32 v53, v98, 0xba800000, v53
	v_pk_mov_b32 v[84:85], v[82:83], v[80:81] op_sel:[1,0]
	v_mov_b32_e32 v83, v81
	v_pk_add_f32 v[80:81], v[84:85], v[82:83]
	v_fmac_f32_e32 v52, 0xba800000, v98
	v_fmamk_f32 v55, v98, 0xba800000, v55
	v_fmac_f32_e32 v54, 0xba800000, v98
	v_pk_add_f32 v[80:81], v[80:81], v[80:81] op_sel_hi:[0,1]
	v_pk_mul_f32 v[82:83], v[54:55], v[54:55]
	v_pk_mul_f32 v[84:85], v[52:53], v[52:53]
	v_fmac_f32_e32 v56, 0xba800000, v98
	v_pk_mov_b32 v[86:87], v[84:85], v[82:83] op_sel:[1,0]
	v_mov_b32_e32 v85, v83
	v_fmamk_f32 v57, v98, 0xba800000, v57
	v_fmac_f32_e32 v58, 0xba800000, v98
	v_mul_f32_e32 v80, v56, v56
	v_pk_add_f32 v[82:83], v[86:87], v[84:85]
	v_fmamk_f32 v59, v98, 0xba800000, v59
	v_pk_fma_f32 v[84:85], v[56:57], v[56:57], v[80:81] op_sel_hi:[1,1,0]
	v_mul_f32_e32 v80, v58, v58
	v_pk_add_f32 v[82:83], v[82:83], v[82:83] op_sel_hi:[0,1]
	v_pk_fma_f32 v[86:87], v[58:59], v[58:59], v[80:81] op_sel_hi:[1,1,0]
	v_fmamk_f32 v63, v98, 0xba800000, v63
	v_fmac_f32_e32 v62, 0xba800000, v98
	v_fmamk_f32 v61, v98, 0xba800000, v61
	v_fmac_f32_e32 v60, 0xba800000, v98
	v_mul_f32_e32 v84, v60, v60
	v_mul_f32_e32 v86, v61, v61
	v_mul_f32_e32 v80, v62, v62
	v_mul_f32_e32 v82, v63, v63
	v_pk_add_f32 v[84:85], v[84:85], v[86:87]
	v_pk_add_f32 v[80:81], v[80:81], v[82:83]
	s_nop 0
	v_pk_add_f32 v[80:81], v[84:85], v[80:81]
	global_load_dwordx4 v[82:85], v94, s[6:7]
	global_load_dwordx4 v[98:101], v94, s[4:5]
	global_load_dwordx4 v[104:107], v95, s[6:7]
	global_load_dwordx4 v[108:111], v95, s[4:5]
	global_load_dwordx4 v[112:115], v96, s[6:7]
	global_load_dwordx4 v[116:119], v96, s[4:5]
	global_load_dwordx4 v[120:123], v97, s[6:7]
	global_load_dwordx4 v[124:127], v97, s[4:5]
	v_add_f32_e32 v80, v80, v81
	ds_bpermute_b32 v81, v88, v80
	s_waitcnt lgkmcnt(0)
; __device__ __forceinline__ unsigned cvt_pk_bf16(float lo, float hi) { unsigned r; asm volatile("s_nop 0\n\tv_cvt_pk_bf16_f32 %0, %1, %2\n\ts_nop 1" : "=v"(r) : "v"(lo), "v"(hi)); return r; }
; __device__ __forceinline__ void phase_ln1(const Params& p, int g, int gw, int NGW, int lane) {
;     ...
;         if (row + NGW < TG) { const size_t nr = (size_t)(row + NGW) * DM;
; #pragma unroll
;             for (int j = 0; j < 4; ++j) { nx[j] = *(const f32x4*)(xbase + nr + 4 * lane + 256 * j); nb[j] = *(const u32x2*)(brbase + nr + 4 * lane + 256 * j); } }
;     ...
;         mean = wave_sum(s, lane) * (1.f / DM); s2 = 0.f;
; #pragma unroll
;         for (int j = 0; j < 4; ++j) { v[j] = v[j] - mean; s2 += (v[j].x * v[j].x + v[j].y * v[j].y) + (v[j].z * v[j].z + v[j].w * v[j].w); }
;         rstd = __builtin_amdgcn_rsqf(wave_sum(s2, lane) * (1.f / DM) + 1e-6f);
; #pragma unroll
;         for (int j = 0; j < 4; ++j) { const int col = 4 * lane + 256 * j; const f32x4 a = *(const f32x4*)(sc + col), bb = *(const f32x4*)(sh + col);
;             const f32x4 o = v[j] * rstd * (a + 1.f) + bb; u32x2 w; w.x = cvt_pk_bf16(o.x, o.y); w.y = cvt_pk_bf16(o.z, o.w);
;             *(u32x2*)(h1 + (size_t)row * DM + col) = w; }
;     }
	v_add_f32_e32 v80, v80, v81
	ds_bpermute_b32 v81, v89, v80
	s_waitcnt lgkmcnt(0)
	v_add_f32_e32 v80, v80, v81
	ds_bpermute_b32 v81, v90, v80
	s_waitcnt lgkmcnt(0)
	v_add_f32_e32 v80, v80, v81
	ds_bpermute_b32 v81, v91, v80
	s_waitcnt lgkmcnt(0)
	v_add_f32_e32 v80, v80, v81
	ds_bpermute_b32 v81, v92, v80
	s_waitcnt lgkmcnt(0)
	v_add_f32_e32 v80, v80, v81
	ds_bpermute_b32 v81, v93, v80
	s_waitcnt lgkmcnt(0)
	v_add_f32_e32 v80, v80, v81
	v_fmamk_f32 v80, v80, 0x3a800000, v238
	v_rsq_f32_e32 v80, v80
	s_waitcnt vmcnt(0)
	v_pk_add_f32 v[84:85], v[84:85], 1.0 op_sel_hi:[1,0]
	v_pk_mul_f32 v[48:49], v[48:49], v[80:81] op_sel_hi:[1,0]
	v_pk_mul_f32 v[50:51], v[50:51], v[80:81] op_sel_hi:[1,0]
	v_pk_add_f32 v[82:83], v[82:83], 1.0 op_sel_hi:[1,0]
	v_pk_fma_f32 v[50:51], v[84:85], v[50:51], v[100:101]
	v_pk_fma_f32 v[48:49], v[82:83], v[48:49], v[98:99]
	v_pk_mul_f32 v[52:53], v[52:53], v[80:81] op_sel_hi:[1,0]
	v_cvt_pk_bf16_f32 v48, v48, v49
	v_cvt_pk_bf16_f32 v49, v50, v51
	v_lshl_add_u64 v[50:51], s[94:95], 0, v[70:71]
	v_add_co_u32_e32 v86, vcc, s1, v50
	v_pk_mul_f32 v[54:55], v[54:55], v[80:81] op_sel_hi:[1,0]
	s_nop 0
	v_addc_co_u32_e32 v87, vcc, 0, v51, vcc
	global_store_dwordx2 v[86:87], v[48:49], off
	s_nop 0
	v_pk_mul_f32 v[56:57], v[56:57], v[80:81] op_sel_hi:[1,0]
	v_pk_mul_f32 v[58:59], v[58:59], v[80:81] op_sel_hi:[1,0]
	s_and_b64 vcc, exec, s[2:3]
	v_pk_add_f32 v[48:49], v[104:105], 1.0 op_sel_hi:[1,0]
	v_pk_add_f32 v[50:51], v[106:107], 1.0 op_sel_hi:[1,0]
	v_pk_fma_f32 v[48:49], v[48:49], v[52:53], v[108:109]
	v_pk_fma_f32 v[50:51], v[50:51], v[54:55], v[110:111]
	v_cvt_pk_bf16_f32 v48, v48, v49
	v_mov_b64_e32 v[82:83], v[74:75]
	v_cvt_pk_bf16_f32 v49, v50, v51
	global_store_dwordx2 v[86:87], v[48:49], off offset:512
	s_nop 0
	v_mov_b64_e32 v[84:85], v[76:77]
	v_pk_add_f32 v[48:49], v[112:113], 1.0 op_sel_hi:[1,0]
	v_pk_add_f32 v[50:51], v[114:115], 1.0 op_sel_hi:[1,0]
	v_pk_fma_f32 v[48:49], v[48:49], v[56:57], v[116:117]
	v_pk_fma_f32 v[50:51], v[50:51], v[58:59], v[118:119]
	v_cvt_pk_bf16_f32 v48, v48, v49
	v_pk_mul_f32 v[56:57], v[60:61], v[80:81] op_sel_hi:[1,0]
	v_cvt_pk_bf16_f32 v49, v50, v51
	global_store_dwordx2 v[86:87], v[48:49], off offset:1024
	s_nop 0
	v_readlane_b32 s4, v255, 2
	v_readlane_b32 s5, v255, 3
	v_pk_mul_f32 v[58:59], v[62:63], v[80:81] op_sel_hi:[1,0]
	v_mov_b64_e32 v[80:81], v[72:73]
	v_lshl_add_u64 v[70:71], v[70:71], 0, s[4:5]
	v_readlane_b32 s4, v255, 0
	v_readlane_b32 s5, v255, 1
	v_mov_b32_e32 v60, v32
	v_mov_b32_e32 v61, v33
	v_lshl_add_u64 v[68:69], v[68:69], 0, s[4:5]
	s_mov_b32 s4, s0
	v_mov_b32_e32 v62, v34
	v_mov_b32_e32 v63, v35
	v_pk_add_f32 v[48:49], v[120:121], 1.0 op_sel_hi:[1,0]
	v_pk_add_f32 v[50:51], v[122:123], 1.0 op_sel_hi:[1,0]
	v_pk_fma_f32 v[48:49], v[48:49], v[56:57], v[124:125]
	v_pk_fma_f32 v[50:51], v[50:51], v[58:59], v[126:127]
	v_cvt_pk_bf16_f32 v48, v48, v49
	v_mov_b32_e32 v56, v36
	v_cvt_pk_bf16_f32 v49, v50, v51
	global_store_dwordx2 v[86:87], v[48:49], off offset:1536
	v_mov_b64_e32 v[86:87], v[78:79]
	v_mov_b32_e32 v57, v37
	v_mov_b32_e32 v58, v38
	v_mov_b32_e32 v59, v39
	v_mov_b32_e32 v52, v40
	v_mov_b32_e32 v53, v41
	v_mov_b32_e32 v54, v42
	v_mov_b32_e32 v55, v43
	v_mov_b32_e32 v48, v44
	v_mov_b32_e32 v49, v45
	v_mov_b32_e32 v50, v46
	v_mov_b32_e32 v51, v47
	s_cbranch_vccnz .LBB0_308
.LBB0_306:
	v_readlane_b32 s0, v255, 12
	s_add_i32 s0, s4, s0
	s_cmpk_gt_i32 s0, 0x7fff
	s_cselect_b64 s[2:3], -1, 0
	s_and_b64 vcc, exec, s[2:3]
	v_mov_b32_e32 v32, v60
	v_mov_b32_e32 v33, v61
	v_mov_b32_e32 v34, v62
	v_mov_b32_e32 v35, v63
	v_mov_b32_e32 v36, v56
	v_mov_b32_e32 v37, v57
	v_mov_b32_e32 v38, v58
	v_mov_b32_e32 v39, v59
	v_mov_b32_e32 v40, v52
	v_mov_b32_e32 v41, v53
	v_mov_b32_e32 v42, v54
	v_mov_b32_e32 v43, v55
	v_mov_b32_e32 v44, v48
	v_mov_b32_e32 v45, v49
	v_mov_b32_e32 v46, v50
	v_mov_b32_e32 v47, v51
	v_readlane_b32 s1, v255, 13
	s_cbranch_vccnz .LBB0_305
	s_ashr_i32 s1, s0, 31
	s_lshl_b64 s[6:7], s[0:1], 12
	v_lshl_add_u64 v[44:45], v[66:67], 0, s[6:7]
	s_lshl_b64 s[6:7], s[0:1], 11
	v_lshl_add_u64 v[72:73], v[64:65], 0, s[6:7]
	global_load_dwordx4 v[32:35], v[44:45], off
	global_load_dwordx4 v[36:39], v[44:45], off offset:1024
	global_load_dwordx4 v[40:43], v[44:45], off offset:2048
	s_nop 0
	global_load_dwordx4 v[44:47], v[44:45], off offset:3072
	s_nop 0
	global_load_dwordx2 v[78:79], v[72:73], off
	global_load_dwordx2 v[76:77], v[72:73], off offset:512
	global_load_dwordx2 v[74:75], v[72:73], off offset:1024
	s_nop 0
	global_load_dwordx2 v[72:73], v[72:73], off offset:1536
	s_branch .LBB0_305

; __device__ __forceinline__ float log1p_small(float e) { return e < 0.03f ? e * (1.f - e * (0.5f - e * (0.33333334f - 0.25f * e))) : __logf(1.f + e); }
; template <int DIR>
; __device__ __forceinline__ void lru_item(const Params& p, int item, int lane) {
;     ...
;     const float ba = p.lru_ba[DIR * 1024 + d], bi = p.lru_bi[DIR * 1024 + d];
;     const float c8 = -8.f * log1p_small(__expf(-p.lru_lambda[DIR * 1024 + d]));
;     const bf16_t* uu = (const bf16_t*)(p.ws + OFF_U);
;     bf16_t* yl = (bf16_t*)(p.ws + (DIR ? OFF_YLB : OFF_YLF));
;     float hst = 0.f;
;     auto tile_row0 = [&](int t) -> size_t { const bool cx = t < 8; const int tl = cx ? (DIR ? 7 - t : t) : (DIR ? 71 - t : t - 8);
;         return cx ? (size_t)bl * 256 + tl * 32 : (size_t)CGR + (size_t)bl * 2048 + tl * 32; };
;     bf16x8 uf[8], ui0, ui1;
;     { const bf16_t* up = uu + (tile_row0(0) + r) * 1024 + blk * 128 + 8 * h;
; #pragma unroll
;       for (int s = 0; s < 8; ++s) uf[s] = ld8(up + 16 * s);
;       ui0 = ld8(up + 32 * db); ui1 = ld8(up + 32 * db + 16); }
.LBB0_477:
	s_andn2_saveexec_b64 s[4:5], s[8:9]
	v_fmamk_f32 v0, v1, 0xbe800000, v237
	v_fma_f32 v0, -v1, v0, 0.5
	v_fma_f32 v0, -v1, v0, 1.0
	v_mul_f32_e32 v0, v1, v0
	s_or_b64 exec, exec, s[4:5]
	s_ashr_i32 s8, s11, 5
	s_ashr_i32 s9, s8, 31
	s_lshl_b64 s[4:5], s[8:9], 8
	v_mov_b32_e32 v3, s5
	v_or_b32_e32 v2, s4, v160
	v_lshlrev_b64 v[2:3], 11, v[2:3]
	v_lshl_add_u64 v[2:3], s[6:7], 0, v[2:3]
	s_lshl_b32 s14, s10, 1
	s_mov_b32 s15, s67
	v_lshl_add_u64 v[2:3], v[2:3], 0, s[14:15]
	v_lshl_add_u64 v[2:3], v[2:3], 0, v[192:193]
	s_mov_b64 s[12:13], 0x70000
	v_lshl_add_u64 v[4:5], v[2:3], 0, s[12:13]
	s_mov_b32 s12, 0x70000
	v_add_co_u32_e32 v2, vcc, s12, v2
	v_lshl_add_u64 v[174:175], v[164:165], 0, s[14:15]
	s_nop 0
	v_addc_co_u32_e32 v3, vcc, 0, v3, vcc
	global_load_dwordx4 v[148:151], v[4:5], off offset:32
	global_load_dwordx4 v[144:147], v[4:5], off offset:64
	global_load_dwordx4 v[140:143], v[4:5], off offset:96
	global_load_dwordx4 v[136:139], v[4:5], off offset:128
	global_load_dwordx4 v[132:135], v[4:5], off offset:160
	global_load_dwordx4 v[128:131], v[4:5], off offset:192
	global_load_dwordx4 v[156:159], v[2:3], off
	global_load_dwordx4 v[124:127], v[4:5], off offset:224
	v_lshl_add_u64 v[2:3], v[4:5], 0, s[66:67]
	global_load_dwordx4 v[152:155], v[2:3], off
	global_load_dwordx4 v[120:123], v[2:3], off offset:32
	s_lshl_b64 s[14:15], s[8:9], 11
	s_add_u32 s13, s14, 0x1000
	v_mul_f32_e32 v0, 0xc1000000, v0
	s_addc_u32 s14, s15, 0
	s_lshl_b64 s[8:9], s[8:9], 22
	v_mul_f32_e32 v176, 0x3fb8aa3b, v0
	v_mov_b32_e32 v1, s9
	v_or_b32_e32 v0, s8, v182
	s_mov_b32 s12, 0
	v_mov_b32_e32 v171, v170
	v_mov_b32_e32 v173, v172
	v_mov_b32_e32 v177, v176
	v_lshl_add_u64 v[178:179], v[166:167], 0, v[0:1]
	v_mov_b32_e32 v183, 0
	s_mov_b64 s[8:9], 0
	s_waitcnt vmcnt(0)
	s_branch .LBB0_481

; __device__ __forceinline__ f32x16 mfma32(bf16x8 a, bf16x8 b, f32x16 c) { return __builtin_amdgcn_mfma_f32_32x32x16_bf16(a, b, c, 0, 0, 0); }
; template <int DIR>
; __device__ __forceinline__ void lru_item(const Params& p, int item, int lane) {
;     ...
;         f32x16 Aa, Ai, Au;
; #pragma unroll
;         for (int e = 0; e < 16; ++e) { Aa[e] = 0.f; Ai[e] = 0.f; Au[e] = 0.f; }
; #pragma unroll
;         for (int s = 0; s < 8; ++s) { Aa = mfma32(uf[s], Wa[s], Aa); Ai = mfma32(uf[s], Wi[s], Ai); }
;         Au = mfma32(ui0, I0, Au); Au = mfma32(ui1, I1, Au);
;         { const int tn = t + 1 < 72 ? t + 1 : 71; const bf16_t* up = uu + (tile_row0(tn) + r) * 1024 + blk * 128 + 8 * h;
; #pragma unroll
;           for (int s = 0; s < 8; ++s) uf[s] = ld8(up + 16 * s);
;           ui0 = ld8(up + 32 * db); ui1 = ld8(up + 32 * db + 16); }
;         float av[16], bv[16];
; #pragma unroll
;         for (int e = 0; e < 16; e += 2) {
;             const f32x2 xa = (f32x2){Aa[e], Aa[e + 1]} + ba, xi = (f32x2){Ai[e], Ai[e + 1]} + bi, uv = (f32x2){Au[e], Au[e + 1]};
;             const f32x2 ta = xa * -1.4426950408889634f, ti = xi * -1.4426950408889634f;
;             f32x2 da, di; da.x = __builtin_amdgcn_exp2f(ta.x); da.y = __builtin_amdgcn_exp2f(ta.y); di.x = __builtin_amdgcn_exp2f(ti.x); di.y = __builtin_amdgcn_exp2f(ti.y);
;             da = da + 1.f; di = di + 1.f;
;             f32x2 ra, ri; ra.x = __builtin_amdgcn_rcpf(da.x); ra.y = __builtin_amdgcn_rcpf(da.y); ri.x = __builtin_amdgcn_rcpf(di.x); ri.y = __builtin_amdgcn_rcpf(di.y);
;             const f32x2 la = ra * (c8 * 1.4426950408889634f);
;             f32x2 a; a.x = __builtin_amdgcn_exp2f(la.x); a.y = __builtin_amdgcn_exp2f(la.y);
.LBB0_481:
	v_mfma_f32_32x32x16_bf16 v[32:47], v[156:159], v[56:59], 0
	v_mov_b64_e32 v[186:187], v[126:127]
	v_mov_b64_e32 v[184:185], v[124:125]
	s_mov_b32 s15, s12
	s_add_i32 s12, s12, 1
	s_cmp_lg_u32 s8, 0xffb90000
	s_cselect_b32 s22, s12, 0x47
	s_cmp_lt_u32 s22, 8
	v_mfma_f32_32x32x16_bf16 v[32:47], v[148:151], v[64:67], v[32:47]
	s_cselect_b64 s[18:19], -1, 0
	s_and_b64 s[20:21], s[18:19], exec
	s_cselect_b32 s20, 7, 0x47
	s_sub_i32 s20, s20, s22
	s_lshl_b32 s20, s20, 5
	s_ashr_i32 s21, s20, 31
	s_and_b64 s[18:19], s[18:19], exec
	v_mfma_f32_32x32x16_bf16 v[16:31], v[156:159], v[60:63], 0
	s_cselect_b32 s19, s4, s13
	s_cselect_b32 s18, s5, s14
	s_add_u32 s19, s19, s20
	s_addc_u32 s18, s18, s21
	v_mov_b32_e32 v125, s18
	v_or_b32_e32 v124, s19, v160
	v_lshlrev_b64 v[124:125], 11, v[124:125]
	v_mfma_f32_32x32x16_bf16 v[32:47], v[144:147], v[72:75], v[32:47]
	s_cmp_lt_u32 s15, 8
	v_mfma_f32_32x32x16_bf16 v[16:31], v[148:151], v[68:71], v[16:31]
	v_mfma_f32_32x32x16_bf16 v[32:47], v[140:143], v[80:83], v[32:47]
	v_mfma_f32_32x32x16_bf16 v[16:31], v[144:147], v[76:79], v[16:31]
	v_mfma_f32_32x32x16_bf16 v[32:47], v[136:139], v[88:91], v[32:47]
	v_mfma_f32_32x32x16_bf16 v[16:31], v[140:143], v[84:87], v[16:31]
	v_mfma_f32_32x32x16_bf16 v[32:47], v[132:135], v[96:99], v[32:47]
	v_mfma_f32_32x32x16_bf16 v[16:31], v[136:139], v[92:95], v[16:31]
	v_mfma_f32_32x32x16_bf16 v[32:47], v[128:131], v[104:107], v[32:47]
	v_mfma_f32_32x32x16_bf16 v[16:31], v[132:135], v[100:103], v[16:31]
	v_mfma_f32_32x32x16_bf16 v[32:47], v[184:187], v[112:115], v[32:47]
	v_mfma_f32_32x32x16_bf16 v[16:31], v[128:131], v[108:111], v[16:31]
	s_nop 10
	v_add_f32_e64 v32, v170, v32
	v_add_f32_e64 v33, v171, v33
	v_add_f32_e64 v34, v170, v34
	v_add_f32_e64 v35, v171, v35
	v_mul_f32_e64 v32, v32, s90
	v_mul_f32_e64 v33, v33, s90
	v_pk_mul_f32 v[34:35], v[34:35], s[90:91] op_sel_hi:[1,0]
	v_exp_f32_e32 v32, v32
	v_exp_f32_e32 v33, v33
	v_exp_f32_e32 v34, v34
	v_mfma_f32_32x32x16_bf16 v[16:31], v[184:187], v[116:119], v[16:31]
	v_exp_f32_e32 v35, v35
	v_pk_add_f32 v[32:33], v[32:33], 1.0 op_sel_hi:[1,0]
	v_pk_add_f32 v[36:37], v[170:171], v[36:37]
	v_rcp_f32_e32 v32, v32
	v_rcp_f32_e32 v33, v33
	v_pk_mul_f32 v[36:37], v[36:37], s[90:91] op_sel_hi:[1,0]
	s_nop 5
	v_pk_add_f32 v[16:17], v[172:173], v[16:17]
	v_mfma_f32_32x32x16_bf16 v[0:15], v[152:155], v[48:51], 0
	v_mul_f32_e64 v16, v16, s90
	v_mul_f32_e64 v17, v17, s90
	v_exp_f32_e32 v36, v36
	v_exp_f32_e32 v184, v16
	v_exp_f32_e32 v185, v17
	v_pk_mul_f32 v[16:17], v[176:177], v[32:33]
	v_exp_f32_e32 v37, v37
	v_exp_f32_e32 v16, v16
	v_exp_f32_e32 v17, v17
	v_mfma_f32_32x32x16_bf16 v[0:15], v[120:123], v[52:55], v[0:15]
	v_add_f32_e64 v32, v184, 1.0
	v_add_f32_e64 v33, v185, 1.0
	v_lshl_add_u64 v[152:153], v[174:175], 0, v[124:125]
	v_fma_f32 v184, -v16, v16, 1.0
	v_fma_f32 v185, -v17, v17, 1.0
	v_rcp_f32_e32 v32, v32
	v_rcp_f32_e32 v33, v33
	v_max_f32_e32 v184, 0, v184
	v_max_f32_e32 v185, 0, v185
	v_sqrt_f32_e32 v184, v184
	v_sqrt_f32_e32 v185, v185
	s_nop 0
	v_pk_mul_f32 v[0:1], v[32:33], v[0:1]
	global_load_dwordx4 v[156:159], v[152:153], off
	global_load_dwordx4 v[148:151], v[152:153], off offset:32
	global_load_dwordx4 v[144:147], v[152:153], off offset:64
	global_load_dwordx4 v[140:143], v[152:153], off offset:96
	global_load_dwordx4 v[136:139], v[152:153], off offset:128
	global_load_dwordx4 v[132:135], v[152:153], off offset:160
	global_load_dwordx4 v[128:131], v[152:153], off offset:192
	global_load_dwordx4 v[124:127], v[152:153], off offset:224
	v_lshl_add_u64 v[120:121], v[152:153], 0, s[66:67]
	v_pk_mul_f32 v[32:33], v[0:1], v[184:185]
	v_pk_add_f32 v[0:1], v[172:173], v[18:19]
	v_pk_add_f32 v[18:19], v[34:35], 1.0 op_sel_hi:[1,0]
	v_pk_mul_f32 v[0:1], v[0:1], s[90:91] op_sel_hi:[1,0]
	v_rcp_f32_e32 v18, v18
	v_rcp_f32_e32 v19, v19
	v_exp_f32_e32 v34, v0
	v_exp_f32_e32 v35, v1
	global_load_dwordx4 v[152:155], v[120:121], off
	s_nop 0
	global_load_dwordx4 v[120:123], v[120:121], off offset:32
	v_pk_mul_f32 v[0:1], v[176:177], v[18:19]
	v_pk_add_f32 v[18:19], v[34:35], 1.0 op_sel_hi:[1,0]
	v_exp_f32_e32 v0, v0
	v_exp_f32_e32 v1, v1
	v_rcp_f32_e32 v18, v18
	v_rcp_f32_e32 v19, v19
	v_pk_fma_f32 v[34:35], v[0:1], v[0:1], 1.0 op_sel_hi:[1,1,0] neg_lo:[1,0,0] neg_hi:[1,0,0]
	s_nop 0
	v_max_f32_e32 v34, 0, v34
	v_max_f32_e32 v35, 0, v35
	v_pk_mul_f32 v[2:3], v[18:19], v[2:3]
	v_pk_add_f32 v[18:19], v[172:173], v[20:21]
	v_pk_add_f32 v[20:21], v[36:37], 1.0 op_sel_hi:[1,0]
	v_sqrt_f32_e32 v34, v34
	v_sqrt_f32_e32 v35, v35
	v_rcp_f32_e32 v20, v20
	v_rcp_f32_e32 v21, v21
	v_pk_mul_f32 v[18:19], v[18:19], s[90:91] op_sel_hi:[1,0]
	v_pk_mul_f32 v[2:3], v[2:3], v[34:35]
	v_exp_f32_e32 v34, v18
	v_exp_f32_e32 v35, v19
	v_pk_mul_f32 v[18:19], v[176:177], v[20:21]
	v_pk_add_f32 v[36:37], v[170:171], v[38:39]
	v_exp_f32_e32 v18, v18
	v_exp_f32_e32 v19, v19
	v_pk_add_f32 v[20:21], v[34:35], 1.0 op_sel_hi:[1,0]
	v_pk_mul_f32 v[36:37], v[36:37], s[90:91] op_sel_hi:[1,0]
	v_rcp_f32_e32 v20, v20
	v_pk_fma_f32 v[34:35], v[18:19], v[18:19], 1.0 op_sel_hi:[1,1,0] neg_lo:[1,0,0] neg_hi:[1,0,0]
	v_rcp_f32_e32 v21, v21
	v_max_f32_e32 v34, 0, v34
	v_max_f32_e32 v35, 0, v35
	v_sqrt_f32_e32 v34, v34
	v_sqrt_f32_e32 v35, v35
	v_exp_f32_e32 v36, v36
	v_exp_f32_e32 v37, v37
	v_pk_mul_f32 v[4:5], v[20:21], v[4:5]
	s_nop 0
	v_pk_mul_f32 v[20:21], v[4:5], v[34:35]
	v_pk_add_f32 v[4:5], v[172:173], v[22:23]
	v_pk_add_f32 v[22:23], v[36:37], 1.0 op_sel_hi:[1,0]
	v_pk_mul_f32 v[4:5], v[4:5], s[90:91] op_sel_hi:[1,0]
	v_rcp_f32_e32 v22, v22
	v_rcp_f32_e32 v23, v23
	v_exp_f32_e32 v34, v4
	v_exp_f32_e32 v35, v5
	v_pk_add_f32 v[36:37], v[170:171], v[40:41]
; template <int DIR>
; __device__ __forceinline__ void lru_item(const Params& p, int item, int lane) {
;     ...
;         for (int e = 0; e < 16; e += 2) {
;             const f32x2 xa = (f32x2){Aa[e], Aa[e + 1]} + ba, xi = (f32x2){Ai[e], Ai[e + 1]} + bi, uv = (f32x2){Au[e], Au[e + 1]};
;             const f32x2 ta = xa * -1.4426950408889634f, ti = xi * -1.4426950408889634f;
;             f32x2 da, di; da.x = __builtin_amdgcn_exp2f(ta.x); da.y = __builtin_amdgcn_exp2f(ta.y); di.x = __builtin_amdgcn_exp2f(ti.x); di.y = __builtin_amdgcn_exp2f(ti.y);
;             da = da + 1.f; di = di + 1.f;
;             f32x2 ra, ri; ra.x = __builtin_amdgcn_rcpf(da.x); ra.y = __builtin_amdgcn_rcpf(da.y); ri.x = __builtin_amdgcn_rcpf(di.x); ri.y = __builtin_amdgcn_rcpf(di.y);
;             const f32x2 la = ra * (c8 * 1.4426950408889634f);
;             f32x2 a; a.x = __builtin_amdgcn_exp2f(la.x); a.y = __builtin_amdgcn_exp2f(la.y);
;             f32x2 om = 1.f - a * a; om.x = fmaxf(om.x, 0.f); om.y = fmaxf(om.y, 0.f);
;             f32x2 sq; sq.x = __builtin_amdgcn_sqrtf(om.x); sq.y = __builtin_amdgcn_sqrtf(om.y);
;             const f32x2 b = sq * (ri * uv);
;             const int k0 = DIR ? 15 - e : e, k1 = DIR ? 14 - e : e + 1;
;             av[k0] = a.x; bv[k0] = b.x; av[k1] = a.y; bv[k1] = b.y;
;         }
;         const int hh = DIR ? 1 - h : h;
;         float Ag[4], Bg[4];
; #pragma unroll
;         for (int q = 0; q < 4; q += 2) {
;             f32x2 A = (f32x2){av[4 * q], av[4 * q + 4]}, B = (f32x2){bv[4 * q], bv[4 * q + 4]};
; #pragma unroll
;             for (int k = 1; k < 4; ++k) { const f32x2 ak = (f32x2){av[4 * q + k], av[4 * q + 4 + k]}, bk = (f32x2){bv[4 * q + k], bv[4 * q + 4 + k]};
;                 A = A * ak; B = B * ak + bk; av[4 * q + k] = A.x; av[4 * q + 4 + k] = A.y; bv[4 * q + k] = B.x; bv[4 * q + 4 + k] = B.y; }
;             Ag[q] = A.x; Ag[q + 1] = A.y; Bg[q] = B.x; Bg[q + 1] = B.y;
;         }
;         float Ap[4], Bp[4];
; #pragma unroll
;         for (int q = 0; q < 4; ++q) { Ap[q] = lane_get(Ag[q], lane ^ 32); Bp[q] = lane_get(Bg[q], lane ^ 32); }
;         float st = hst, hs[4];
; #pragma unroll
;         for (int Gi = 0; Gi < 8; ++Gi) {
;             const int q = Gi >> 1; const bool own = (hh == (Gi & 1));
;             const float A = own ? Ag[q] : Ap[q], B = own ? Bg[q] : Bp[q];
;             if (own) hs[q] = st;
	v_pk_mul_f32 v[4:5], v[176:177], v[22:23]
	v_pk_mul_f32 v[36:37], v[36:37], s[90:91] op_sel_hi:[1,0]
	v_pk_add_f32 v[22:23], v[34:35], 1.0 op_sel_hi:[1,0]
	v_exp_f32_e32 v4, v4
	v_exp_f32_e32 v5, v5
	v_rcp_f32_e32 v22, v22
	v_rcp_f32_e32 v23, v23
	v_exp_f32_e32 v36, v36
	v_exp_f32_e32 v37, v37
	v_pk_fma_f32 v[34:35], v[4:5], v[4:5], 1.0 op_sel_hi:[1,1,0] neg_lo:[1,0,0] neg_hi:[1,0,0]
	v_pk_mul_f32 v[6:7], v[22:23], v[6:7]
	v_pk_add_f32 v[22:23], v[172:173], v[24:25]
	v_pk_add_f32 v[24:25], v[36:37], 1.0 op_sel_hi:[1,0]
	v_max_f32_e32 v34, 0, v34
	v_max_f32_e32 v35, 0, v35
	v_rcp_f32_e32 v24, v24
	v_rcp_f32_e32 v25, v25
	v_sqrt_f32_e32 v34, v34
	v_sqrt_f32_e32 v35, v35
	v_pk_mul_f32 v[22:23], v[22:23], s[90:91] op_sel_hi:[1,0]
	v_pk_mul_f32 v[24:25], v[176:177], v[24:25]
	v_exp_f32_e32 v22, v22
	v_exp_f32_e32 v23, v23
	v_pk_mul_f32 v[6:7], v[6:7], v[34:35]
	v_exp_f32_e32 v34, v24
	v_exp_f32_e32 v35, v25
	v_pk_add_f32 v[36:37], v[170:171], v[42:43]
	v_pk_add_f32 v[22:23], v[22:23], 1.0 op_sel_hi:[1,0]
	v_pk_mul_f32 v[36:37], v[36:37], s[90:91] op_sel_hi:[1,0]
	v_rcp_f32_e32 v22, v22
	v_rcp_f32_e32 v23, v23
	v_exp_f32_e32 v36, v36
	v_exp_f32_e32 v37, v37
	v_pk_fma_f32 v[24:25], v[34:35], v[34:35], 1.0 op_sel_hi:[1,1,0] neg_lo:[1,0,0] neg_hi:[1,0,0]
	v_pk_mul_f32 v[8:9], v[22:23], v[8:9]
	v_max_f32_e32 v24, 0, v24
	v_max_f32_e32 v25, 0, v25
	v_sqrt_f32_e32 v24, v24
	v_sqrt_f32_e32 v25, v25
	v_pk_add_f32 v[22:23], v[36:37], 1.0 op_sel_hi:[1,0]
	v_mov_b32_e32 v42, v6
	v_rcp_f32_e32 v22, v22
	v_rcp_f32_e32 v23, v23
	v_pk_mul_f32 v[38:39], v[8:9], v[24:25]
	v_pk_add_f32 v[8:9], v[172:173], v[26:27]
	v_pk_add_f32 v[26:27], v[170:171], v[44:45]
	v_pk_mul_f32 v[8:9], v[8:9], s[90:91] op_sel_hi:[1,0]
	v_pk_mul_f32 v[26:27], v[26:27], s[90:91] op_sel_hi:[1,0]
	v_exp_f32_e32 v24, v8
	v_exp_f32_e32 v25, v9
	v_pk_mul_f32 v[8:9], v[176:177], v[22:23]
	v_exp_f32_e32 v26, v26
	v_exp_f32_e32 v8, v8
	v_exp_f32_e32 v9, v9
	v_pk_add_f32 v[22:23], v[24:25], 1.0 op_sel_hi:[1,0]
	v_exp_f32_e32 v27, v27
	v_rcp_f32_e32 v22, v22
	v_pk_fma_f32 v[24:25], v[8:9], v[8:9], 1.0 op_sel_hi:[1,1,0] neg_lo:[1,0,0] neg_hi:[1,0,0]
	v_rcp_f32_e32 v23, v23
	v_max_f32_e32 v24, 0, v24
	v_max_f32_e32 v25, 0, v25
	v_sqrt_f32_e32 v24, v24
	v_sqrt_f32_e32 v25, v25
	v_pk_mul_f32 v[10:11], v[22:23], v[10:11]
	v_pk_add_f32 v[22:23], v[172:173], v[28:29]
	v_pk_add_f32 v[28:29], v[172:173], v[30:31]
	v_pk_mul_f32 v[10:11], v[10:11], v[24:25]
	v_pk_add_f32 v[24:25], v[26:27], 1.0 op_sel_hi:[1,0]
	v_pk_mul_f32 v[22:23], v[22:23], s[90:91] op_sel_hi:[1,0]
	v_rcp_f32_e32 v24, v24
	v_rcp_f32_e32 v25, v25
	v_exp_f32_e32 v22, v22
	v_exp_f32_e32 v23, v23
	v_pk_mul_f32 v[28:29], v[28:29], s[90:91] op_sel_hi:[1,0]
	v_pk_mul_f32 v[24:25], v[176:177], v[24:25]
	v_exp_f32_e32 v28, v28
	v_exp_f32_e32 v36, v24
	v_exp_f32_e32 v37, v25
	v_pk_add_f32 v[22:23], v[22:23], 1.0 op_sel_hi:[1,0]
	v_exp_f32_e32 v29, v29
	v_rcp_f32_e32 v24, v22
	v_rcp_f32_e32 v25, v23
	v_pk_fma_f32 v[22:23], v[36:37], v[36:37], 1.0 op_sel_hi:[1,1,0] neg_lo:[1,0,0] neg_hi:[1,0,0]
	v_pk_add_f32 v[28:29], v[28:29], 1.0 op_sel_hi:[1,0]
	v_max_f32_e32 v26, 0, v22
	v_max_f32_e32 v27, 0, v23
	v_pk_add_f32 v[22:23], v[170:171], v[46:47]
	v_sqrt_f32_e32 v26, v26
	v_pk_mul_f32 v[22:23], v[22:23], s[90:91] op_sel_hi:[1,0]
	v_sqrt_f32_e32 v27, v27
	v_exp_f32_e32 v22, v22
	v_exp_f32_e32 v23, v23
	v_rcp_f32_e32 v28, v28
	v_rcp_f32_e32 v29, v29
	v_pk_mul_f32 v[12:13], v[24:25], v[12:13]
	v_pk_add_f32 v[22:23], v[22:23], 1.0 op_sel_hi:[1,0]
	v_pk_mul_f32 v[40:41], v[12:13], v[26:27]
	v_rcp_f32_e32 v22, v22
	v_rcp_f32_e32 v23, v23
	v_pk_mul_f32 v[12:13], v[28:29], v[14:15]
	v_mov_b32_e32 v15, v9
	v_mov_b32_e32 v25, v11
	v_pk_mul_f32 v[22:23], v[176:177], v[22:23]
	v_mov_b32_e32 v27, v8
	v_exp_f32_e32 v22, v22
	v_exp_f32_e32 v23, v23
	v_mov_b32_e32 v29, v10
	v_mov_b32_e32 v43, v2
	v_mov_b32_e32 v26, v22
	v_pk_fma_f32 v[30:31], v[22:23], v[22:23], 1.0 op_sel_hi:[1,1,0] neg_lo:[1,0,0] neg_hi:[1,0,0]
	v_mov_b32_e32 v14, v23
	v_max_f32_e32 v30, 0, v30
	v_max_f32_e32 v31, 0, v31
	v_sqrt_f32_e32 v30, v30
	v_sqrt_f32_e32 v31, v31
	v_pk_mul_f32 v[14:15], v[14:15], v[26:27]
	v_mov_b32_e32 v44, v21
	v_mov_b32_e32 v45, v33
	v_pk_mul_f32 v[12:13], v[12:13], v[30:31]
	v_mov_b32_e32 v30, v41
	v_mov_b32_e32 v24, v13
	v_mov_b32_e32 v28, v12
	v_pk_fma_f32 v[24:25], v[26:27], v[24:25], v[28:29]
	v_mov_b32_e32 v28, v37
	v_mov_b32_e32 v29, v35
	v_mov_b32_e32 v31, v39
	v_pk_mul_f32 v[26:27], v[28:29], v[14:15]
	v_pk_fma_f32 v[28:29], v[28:29], v[24:25], v[30:31]
	v_mov_b32_e32 v37, v34
	v_mov_b32_e32 v41, v38
	v_pk_mul_f32 v[30:31], v[36:37], v[26:27]
	v_pk_fma_f32 v[34:35], v[36:37], v[28:29], v[40:41]
	v_mov_b32_e32 v36, v5
	v_mov_b32_e32 v37, v1
	v_mov_b32_e32 v38, v7
	v_mov_b32_e32 v39, v3
	v_mov_b32_e32 v40, v4
	v_mov_b32_e32 v41, v0
	v_pk_mul_f32 v[36:37], v[36:37], v[40:41]
	v_pk_fma_f32 v[38:39], v[40:41], v[38:39], v[42:43]
	v_mov_b32_e32 v42, v19
	v_mov_b32_e32 v43, v17
	ds_bpermute_b32 v4, v180, v30
	ds_bpermute_b32 v8, v180, v34
	v_pk_mul_f32 v[40:41], v[42:43], v[36:37]
	v_pk_fma_f32 v[42:43], v[42:43], v[38:39], v[44:45]
	v_mov_b32_e32 v19, v16
	v_mov_b32_e32 v21, v32
	v_pk_mul_f32 v[16:17], v[18:19], v[40:41]
	v_pk_fma_f32 v[18:19], v[18:19], v[42:43], v[20:21]
	ds_bpermute_b32 v12, v180, v31
	ds_bpermute_b32 v20, v180, v35
	ds_bpermute_b32 v21, v180, v16
	ds_bpermute_b32 v22, v180, v18
	s_waitcnt lgkmcnt(0)
	v_cndmask_b32_e64 v10, v30, v4, s[2:3]
	v_cndmask_b32_e64 v6, v34, v8, s[2:3]
	ds_bpermute_b32 v0, v180, v17
	ds_bpermute_b32 v2, v180, v19
	v_fmac_f32_e32 v6, v183, v10
	v_cndmask_b32_e64 v4, v4, v30, s[2:3]
	v_cndmask_b32_e64 v8, v8, v34, s[2:3]
	v_fmac_f32_e32 v8, v4, v6
	v_cndmask_b32_e64 v4, v31, v12, s[2:3]
	v_cndmask_b32_e64 v10, v35, v20, s[2:3]
	v_fmac_f32_e32 v10, v4, v8
	v_cndmask_b32_e64 v4, v12, v31, s[2:3]
	v_cndmask_b32_e64 v12, v20, v35, s[2:3]
	v_fmac_f32_e32 v12, v4, v10
	v_cndmask_b32_e64 v4, v16, v21, s[2:3]
	v_cndmask_b32_e64 v20, v18, v22, s[2:3]
	v_fmac_f32_e32 v20, v4, v12
	v_cndmask_b32_e64 v4, v21, v16, s[2:3]
	v_cndmask_b32_e64 v21, v22, v18, s[2:3]
	v_fmac_f32_e32 v21, v4, v20
	s_waitcnt lgkmcnt(1)
	v_cndmask_b32_e64 v22, v17, v0, s[2:3]
	s_waitcnt lgkmcnt(0)
	v_cndmask_b32_e64 v4, v19, v2, s[2:3]
	v_fmac_f32_e32 v4, v22, v21
	s_waitcnt vmcnt(0)
	s_cbranch_scc1 .LBB0_480
; __device__ __forceinline__ unsigned short f2bf(float f) { return (unsigned short)(cvt_pk_bf16(f, 0.f) & 0xffffu); }
; template <int DIR>
; __device__ __forceinline__ void lru_item(const Params& p, int item, int lane) {
;     ...
;         float st = hst, hs[4];
; #pragma unroll
;         for (int Gi = 0; Gi < 8; ++Gi) {
;             const int q = Gi >> 1; const bool own = (hh == (Gi & 1));
;             const float A = own ? Ag[q] : Ap[q], B = own ? Bg[q] : Bp[q];
;             if (own) hs[q] = st;
;             st = A * st + B;
;         }
;         hst = st;
;         if (!is_ctx) {
;             bf16_t* yr = yl + ((size_t)bl * 2048 + tile * 32) * 1024 + d;
; #pragma unroll
;             for (int e = 0; e < 16; ++e) { const int k = DIR ? 15 - e : e; const float hv = av[k] * hs[k >> 2] + bv[k];
;                 const int tok = (e & 3) + 8 * (e >> 2) + 4 * h; yr[(size_t)tok * 1024] = f2bf(hv); }
;         }
	v_cndmask_b32_e64 v22, v21, v4, s[2:3]
	v_cndmask_b32_e64 v12, v12, v20, s[2:3]
	v_lshl_add_u64 v[20:21], v[178:179], 0, s[8:9]
	s_mov_b32 s15, 0x1bd70000
	v_add_co_u32_e32 v32, vcc, s15, v20
	s_mov_b32 s15, 0x1bd71000
	s_nop 0
	v_addc_co_u32_e32 v33, vcc, 0, v21, vcc
	v_cndmask_b32_e64 v8, v8, v10, s[2:3]
	v_cndmask_b32_e64 v10, v183, v6, s[2:3]
	v_fma_f32 v6, v17, v22, v19
	v_add_co_u32_e32 v44, vcc, s15, v20
	v_cvt_pk_bf16_f32 v6, v6, v193
	s_mov_b32 s15, 0x1bd74000
	s_nop 0
	v_addc_co_u32_e32 v45, vcc, 0, v21, vcc
	global_store_short v[44:45], v6, off offset:-4096
	v_fma_f32 v6, v41, v22, v43
	v_cvt_pk_bf16_f32 v6, v6, v193
	global_store_short v[32:33], v6, off offset:2048
	v_fma_f32 v6, v37, v22, v39
	v_add_co_u32_e32 v32, vcc, s15, v20
	v_cvt_pk_bf16_f32 v6, v6, v193
	global_store_short v[44:45], v6, off
	v_fmac_f32_e32 v3, v1, v22
	v_cvt_pk_bf16_f32 v1, v3, v193
	v_addc_co_u32_e32 v33, vcc, 0, v21, vcc
	s_mov_b32 s15, 0x1bd75000
	global_store_short v[44:45], v1, off offset:2048
	v_fma_f32 v1, v16, v12, v18
	v_add_co_u32_e32 v44, vcc, s15, v20
	v_cvt_pk_bf16_f32 v1, v1, v193
	v_fmac_f32_e32 v42, v40, v12
	s_nop 0
	v_addc_co_u32_e32 v45, vcc, 0, v21, vcc
	global_store_short v[44:45], v1, off offset:-4096
	v_cvt_pk_bf16_f32 v1, v42, v193
	s_mov_b32 s15, 0x1bd78000
	global_store_short v[32:33], v1, off offset:2048
	v_fmac_f32_e32 v38, v36, v12
	v_cvt_pk_bf16_f32 v1, v38, v193
	v_fmac_f32_e32 v7, v5, v12
	v_add_co_u32_e32 v6, vcc, s15, v20
	global_store_short v[44:45], v1, off
	v_cvt_pk_bf16_f32 v1, v7, v193
	s_nop 0
	v_addc_co_u32_e32 v7, vcc, 0, v21, vcc
	s_mov_b32 s15, 0x1bd79000
	global_store_short v[44:45], v1, off offset:2048
	v_fma_f32 v1, v31, v8, v35
	v_add_co_u32_e32 v32, vcc, s15, v20
	v_cvt_pk_bf16_f32 v1, v1, v193
	v_fmac_f32_e32 v11, v9, v8
	s_nop 0
	v_addc_co_u32_e32 v33, vcc, 0, v21, vcc
	global_store_short v[32:33], v1, off offset:-4096
	v_fma_f32 v1, v27, v8, v29
	v_cvt_pk_bf16_f32 v1, v1, v193
	global_store_short v[6:7], v1, off offset:2048
	v_fma_f32 v1, v15, v8, v25
	v_cvt_pk_bf16_f32 v1, v1, v193
	global_store_short v[32:33], v1, off
	v_cvt_pk_bf16_f32 v1, v11, v193
	v_add_co_u32_e32 v6, vcc, 0x1bd7c000, v20
	global_store_short v[32:33], v1, off offset:2048
	v_fmac_f32_e32 v34, v30, v10
	v_cvt_pk_bf16_f32 v1, v34, v193
	v_addc_co_u32_e32 v7, vcc, 0, v21, vcc
	global_store_short v[6:7], v1, off
	v_fmac_f32_e32 v28, v26, v10
	v_cvt_pk_bf16_f32 v1, v28, v193
	global_store_short v[6:7], v1, off offset:2048
	v_add_co_u32_e32 v6, vcc, 0x1bd7d000, v20
	v_fmac_f32_e32 v24, v14, v10
	v_cvt_pk_bf16_f32 v1, v24, v193
	s_nop 0
	v_addc_co_u32_e32 v7, vcc, 0, v21, vcc
	global_store_short v[6:7], v1, off
	v_fmac_f32_e32 v13, v23, v10
	v_cvt_pk_bf16_f32 v1, v13, v193
	s_nop 1
	global_store_short v[6:7], v1, off offset:2048
	s_branch .LBB0_480

; __device__ __forceinline__ float log1p_small(float e) { return e < 0.03f ? e * (1.f - e * (0.5f - e * (0.33333334f - 0.25f * e))) : __logf(1.f + e); }
; template <int DIR>
; __device__ __forceinline__ void lru_item(const Params& p, int item, int lane) {
;     ...
;     const float ba = p.lru_ba[DIR * 1024 + d], bi = p.lru_bi[DIR * 1024 + d];
;     const float c8 = -8.f * log1p_small(__expf(-p.lru_lambda[DIR * 1024 + d]));
;     const bf16_t* uu = (const bf16_t*)(p.ws + OFF_U);
;     bf16_t* yl = (bf16_t*)(p.ws + (DIR ? OFF_YLB : OFF_YLF));
;     float hst = 0.f;
;     auto tile_row0 = [&](int t) -> size_t { const bool cx = t < 8; const int tl = cx ? (DIR ? 7 - t : t) : (DIR ? 71 - t : t - 8);
;         return cx ? (size_t)bl * 256 + tl * 32 : (size_t)CGR + (size_t)bl * 2048 + tl * 32; };
;     bf16x8 uf[8], ui0, ui1;
;     { const bf16_t* up = uu + (tile_row0(0) + r) * 1024 + blk * 128 + 8 * h;
; #pragma unroll
;       for (int s = 0; s < 8; ++s) uf[s] = ld8(up + 16 * s);
;       ui0 = ld8(up + 32 * db); ui1 = ld8(up + 32 * db + 16); }
.LBB0_487:
	s_andn2_saveexec_b64 s[4:5], s[8:9]
	v_fmamk_f32 v0, v1, 0xbe800000, v237
	v_fma_f32 v0, -v1, v0, 0.5
	v_fma_f32 v0, -v1, v0, 1.0
	v_mul_f32_e32 v0, v1, v0
	s_or_b64 exec, exec, s[4:5]
	s_ashr_i32 s12, s11, 5
	s_ashr_i32 s13, s12, 31
	s_lshl_b64 s[4:5], s[12:13], 8
	v_mov_b32_e32 v3, s5
	v_or_b32_e32 v2, s4, v160
	v_lshlrev_b64 v[2:3], 11, v[2:3]
	v_lshl_add_u64 v[2:3], s[6:7], 0, v[2:3]
	s_lshl_b32 s8, s10, 1
	s_mov_b32 s9, s67
	v_lshl_add_u64 v[2:3], v[2:3], 0, s[8:9]
	v_lshl_add_u64 v[2:3], v[2:3], 0, v[192:193]
	global_load_dwordx4 v[152:155], v[2:3], off
	global_load_dwordx4 v[148:151], v[2:3], off offset:32
	global_load_dwordx4 v[144:147], v[2:3], off offset:64
	global_load_dwordx4 v[136:139], v[2:3], off offset:96
	global_load_dwordx4 v[132:135], v[2:3], off offset:128
	global_load_dwordx4 v[128:131], v[2:3], off offset:160
	global_load_dwordx4 v[124:127], v[2:3], off offset:192
	global_load_dwordx4 v[120:123], v[2:3], off offset:224
	v_lshl_add_u64 v[2:3], v[2:3], 0, s[66:67]
	global_load_dwordx4 v[156:159], v[2:3], off
	global_load_dwordx4 v[140:143], v[2:3], off offset:32
	v_mul_f32_e32 v0, 0xc1000000, v0
	s_lshl_b64 s[10:11], s[12:13], 22
	v_mul_f32_e32 v174, 0x3fb8aa3b, v0
	v_mov_b32_e32 v1, s11
	v_or_b32_e32 v0, s10, v182
	v_lshl_add_u64 v[172:173], v[164:165], 0, s[8:9]
	v_mov_b32_e32 v169, v168
	v_mov_b32_e32 v171, v170
	v_mov_b32_e32 v175, v174
	s_lshl_b64 s[8:9], s[12:13], 11
	v_lshl_add_u64 v[176:177], v[166:167], 0, v[0:1]
	s_mov_b32 s19, 0
	v_mov_b32_e32 v178, 0
	s_mov_b64 s[10:11], 0
	s_waitcnt vmcnt(0)
	s_branch .LBB0_491

; __device__ __forceinline__ f32x16 mfma32(bf16x8 a, bf16x8 b, f32x16 c) { return __builtin_amdgcn_mfma_f32_32x32x16_bf16(a, b, c, 0, 0, 0); }
; template <int DIR>
; __device__ __forceinline__ void lru_item(const Params& p, int item, int lane) {
;     ...
;         f32x16 Aa, Ai, Au;
; #pragma unroll
;         for (int e = 0; e < 16; ++e) { Aa[e] = 0.f; Ai[e] = 0.f; Au[e] = 0.f; }
; #pragma unroll
;         for (int s = 0; s < 8; ++s) { Aa = mfma32(uf[s], Wa[s], Aa); Ai = mfma32(uf[s], Wi[s], Ai); }
;         Au = mfma32(ui0, I0, Au); Au = mfma32(ui1, I1, Au);
.LBB0_491:
	v_mfma_f32_32x32x16_bf16 v[32:47], v[152:155], v[56:59], 0
	s_add_i32 s18, s19, 1
	s_cmp_lg_u32 s10, 0x470000
	s_cselect_b32 s12, s18, 0x47
	s_lshl_b32 s20, s12, 5
	s_cmp_gt_u32 s12, 7
	s_mov_b64 s[14:15], -1
	v_mfma_f32_32x32x16_bf16 v[16:31], v[152:155], v[60:63], 0
	v_mfma_f32_32x32x16_bf16 v[32:47], v[148:151], v[64:67], v[32:47]
	v_mfma_f32_32x32x16_bf16 v[16:31], v[148:151], v[68:71], v[16:31]
	v_mfma_f32_32x32x16_bf16 v[32:47], v[144:147], v[72:75], v[32:47]
	v_mfma_f32_32x32x16_bf16 v[16:31], v[144:147], v[76:79], v[16:31]
	v_mfma_f32_32x32x16_bf16 v[32:47], v[136:139], v[80:83], v[32:47]
	v_mfma_f32_32x32x16_bf16 v[16:31], v[136:139], v[84:87], v[16:31]
	v_mfma_f32_32x32x16_bf16 v[32:47], v[132:135], v[88:91], v[32:47]
	v_mfma_f32_32x32x16_bf16 v[16:31], v[132:135], v[92:95], v[16:31]
	v_mfma_f32_32x32x16_bf16 v[32:47], v[128:131], v[96:99], v[32:47]
	v_mfma_f32_32x32x16_bf16 v[16:31], v[128:131], v[100:103], v[16:31]
	v_mfma_f32_32x32x16_bf16 v[32:47], v[124:127], v[104:107], v[32:47]
	v_mfma_f32_32x32x16_bf16 v[16:31], v[124:127], v[108:111], v[16:31]
	v_mfma_f32_32x32x16_bf16 v[0:15], v[156:159], v[48:51], 0
	v_mfma_f32_32x32x16_bf16 v[32:47], v[120:123], v[112:115], v[32:47]
	v_mfma_f32_32x32x16_bf16 v[16:31], v[120:123], v[116:119], v[16:31]
	v_mfma_f32_32x32x16_bf16 v[0:15], v[140:143], v[52:55], v[0:15]
	s_cbranch_scc0 .LBB0_493
	s_add_i32 s12, s20, 0xf00
	s_add_u32 s12, s8, s12
	s_addc_u32 s13, s9, 0
	s_mov_b64 s[14:15], 0

; template <int DIR>
; __device__ __forceinline__ void lru_item(const Params& p, int item, int lane) {
;     ...
;         { const int tn = t + 1 < 72 ? t + 1 : 71; const bf16_t* up = uu + (tile_row0(tn) + r) * 1024 + blk * 128 + 8 * h;
; #pragma unroll
;           for (int s = 0; s < 8; ++s) uf[s] = ld8(up + 16 * s);
;           ui0 = ld8(up + 32 * db); ui1 = ld8(up + 32 * db + 16); }
;         float av[16], bv[16];
; #pragma unroll
;         for (int e = 0; e < 16; e += 2) {
;             const f32x2 xa = (f32x2){Aa[e], Aa[e + 1]} + ba, xi = (f32x2){Ai[e], Ai[e + 1]} + bi, uv = (f32x2){Au[e], Au[e + 1]};
;             const f32x2 ta = xa * -1.4426950408889634f, ti = xi * -1.4426950408889634f;
;             f32x2 da, di; da.x = __builtin_amdgcn_exp2f(ta.x); da.y = __builtin_amdgcn_exp2f(ta.y); di.x = __builtin_amdgcn_exp2f(ti.x); di.y = __builtin_amdgcn_exp2f(ti.y);
;             da = da + 1.f; di = di + 1.f;
;             f32x2 ra, ri; ra.x = __builtin_amdgcn_rcpf(da.x); ra.y = __builtin_amdgcn_rcpf(da.y); ri.x = __builtin_amdgcn_rcpf(di.x); ri.y = __builtin_amdgcn_rcpf(di.y);
;             const f32x2 la = ra * (c8 * 1.4426950408889634f);
;             f32x2 a; a.x = __builtin_amdgcn_exp2f(la.x); a.y = __builtin_amdgcn_exp2f(la.y);
;             f32x2 om = 1.f - a * a; om.x = fmaxf(om.x, 0.f); om.y = fmaxf(om.y, 0.f);
;             f32x2 sq; sq.x = __builtin_amdgcn_sqrtf(om.x); sq.y = __builtin_amdgcn_sqrtf(om.y);
;             const f32x2 b = sq * (ri * uv);
;             const int k0 = DIR ? 15 - e : e, k1 = DIR ? 14 - e : e + 1;
;             av[k0] = a.x; bv[k0] = b.x; av[k1] = a.y; bv[k1] = b.y;
;         }
.LBB0_495:
	s_nop 6
	v_pk_add_f32 v[32:33], v[168:169], v[32:33]
	v_pk_add_f32 v[16:17], v[170:171], v[16:17]
	v_pk_mul_f32 v[32:33], v[32:33], s[90:91] op_sel_hi:[1,0]
	v_pk_mul_f32 v[16:17], v[16:17], s[90:91] op_sel_hi:[1,0]
	v_exp_f32_e32 v32, v32
	v_exp_f32_e32 v33, v33
	v_exp_f32_e32 v182, v16
	v_exp_f32_e32 v183, v17
	v_pk_add_f32 v[34:35], v[168:169], v[34:35]
	v_pk_add_f32 v[32:33], v[32:33], 1.0 op_sel_hi:[1,0]
	v_pk_mul_f32 v[34:35], v[34:35], s[90:91] op_sel_hi:[1,0]
	v_rcp_f32_e32 v32, v32
	v_rcp_f32_e32 v33, v33
	v_exp_f32_e32 v34, v34
	v_exp_f32_e32 v35, v35
	v_pk_add_f32 v[18:19], v[170:171], v[18:19]
	v_pk_mul_f32 v[16:17], v[174:175], v[32:33]
	v_pk_add_f32 v[32:33], v[182:183], 1.0 op_sel_hi:[1,0]
	v_pk_mul_f32 v[18:19], v[18:19], s[90:91] op_sel_hi:[1,0]
	v_rcp_f32_e32 v32, v32
	v_rcp_f32_e32 v33, v33
	v_pk_add_f32 v[36:37], v[168:169], v[36:37]
	v_lshl_add_u64 v[120:121], s[12:13], 0, v[160:161]
	v_pk_mul_f32 v[36:37], v[36:37], s[90:91] op_sel_hi:[1,0]
	v_pk_mul_f32 v[0:1], v[0:1], v[32:33]
	v_pk_add_f32 v[32:33], v[34:35], 1.0 op_sel_hi:[1,0]
	v_exp_f32_e32 v34, v18
	v_rcp_f32_e32 v32, v32
	v_rcp_f32_e32 v33, v33
	v_exp_f32_e32 v35, v19
	v_exp_f32_e32 v36, v36
	v_exp_f32_e32 v37, v37
	v_pk_mul_f32 v[18:19], v[174:175], v[32:33]
	v_pk_add_f32 v[32:33], v[34:35], 1.0 op_sel_hi:[1,0]
	v_exp_f32_e32 v18, v18
	v_exp_f32_e32 v19, v19
	v_rcp_f32_e32 v32, v32
	v_rcp_f32_e32 v33, v33
	v_lshlrev_b64 v[120:121], 11, v[120:121]
	v_pk_fma_f32 v[34:35], v[18:19], v[18:19], 1.0 op_sel_hi:[1,1,0] neg_lo:[1,0,0] neg_hi:[1,0,0]
	v_lshl_add_u64 v[140:141], v[172:173], 0, v[120:121]
	v_max_f32_e32 v34, 0, v34
	v_max_f32_e32 v35, 0, v35
	v_sqrt_f32_e32 v34, v34
	v_sqrt_f32_e32 v35, v35
	v_pk_mul_f32 v[2:3], v[2:3], v[32:33]
	global_load_dwordx4 v[152:155], v[140:141], off
	global_load_dwordx4 v[148:151], v[140:141], off offset:32
	global_load_dwordx4 v[144:147], v[140:141], off offset:64
	global_load_dwordx4 v[136:139], v[140:141], off offset:96
	global_load_dwordx4 v[132:135], v[140:141], off offset:128
	global_load_dwordx4 v[128:131], v[140:141], off offset:160
	global_load_dwordx4 v[124:127], v[140:141], off offset:192
	global_load_dwordx4 v[120:123], v[140:141], off offset:224
	v_lshl_add_u64 v[140:141], v[140:141], 0, s[66:67]
	v_pk_mul_f32 v[32:33], v[2:3], v[34:35]
	v_pk_add_f32 v[2:3], v[170:171], v[20:21]
	v_pk_add_f32 v[20:21], v[36:37], 1.0 op_sel_hi:[1,0]
	v_pk_mul_f32 v[2:3], v[2:3], s[90:91] op_sel_hi:[1,0]
	v_rcp_f32_e32 v20, v20
	v_rcp_f32_e32 v21, v21
	v_exp_f32_e32 v34, v2
	v_exp_f32_e32 v35, v3
	v_pk_add_f32 v[36:37], v[168:169], v[38:39]
	v_pk_mul_f32 v[2:3], v[174:175], v[20:21]
	v_pk_mul_f32 v[36:37], v[36:37], s[90:91] op_sel_hi:[1,0]
	v_pk_add_f32 v[20:21], v[34:35], 1.0 op_sel_hi:[1,0]
	v_exp_f32_e32 v36, v36
	v_rcp_f32_e32 v20, v20
	v_rcp_f32_e32 v21, v21
	v_exp_f32_e32 v37, v37
	v_exp_f32_e32 v2, v2
	v_exp_f32_e32 v3, v3
	v_pk_mul_f32 v[4:5], v[4:5], v[20:21]
	v_pk_add_f32 v[20:21], v[170:171], v[22:23]
	v_pk_add_f32 v[22:23], v[36:37], 1.0 op_sel_hi:[1,0]
	v_pk_fma_f32 v[34:35], v[2:3], v[2:3], 1.0 op_sel_hi:[1,1,0] neg_lo:[1,0,0] neg_hi:[1,0,0]
	v_rcp_f32_e32 v22, v22
	v_rcp_f32_e32 v23, v23
	v_max_f32_e32 v34, 0, v34
	v_max_f32_e32 v35, 0, v35
	v_pk_mul_f32 v[20:21], v[20:21], s[90:91] op_sel_hi:[1,0]
	v_pk_mul_f32 v[22:23], v[174:175], v[22:23]
	v_sqrt_f32_e32 v34, v34
	v_sqrt_f32_e32 v35, v35
	v_exp_f32_e32 v20, v20
	v_exp_f32_e32 v21, v21
	v_exp_f32_e32 v22, v22
	v_exp_f32_e32 v23, v23
	global_load_dwordx4 v[156:159], v[140:141], off
	s_nop 0
	global_load_dwordx4 v[140:143], v[140:141], off offset:32
	v_pk_mul_f32 v[4:5], v[4:5], v[34:35]
	v_pk_add_f32 v[20:21], v[20:21], 1.0 op_sel_hi:[1,0]
	v_pk_fma_f32 v[34:35], v[22:23], v[22:23], 1.0 op_sel_hi:[1,1,0] neg_lo:[1,0,0] neg_hi:[1,0,0]
	v_rcp_f32_e32 v20, v20
	v_rcp_f32_e32 v21, v21
	v_max_f32_e32 v34, 0, v34
	v_max_f32_e32 v35, 0, v35
	v_pk_add_f32 v[36:37], v[168:169], v[40:41]
	v_sqrt_f32_e32 v34, v34
	v_sqrt_f32_e32 v35, v35
	v_pk_mul_f32 v[36:37], v[36:37], s[90:91] op_sel_hi:[1,0]
	v_pk_mul_f32 v[6:7], v[6:7], v[20:21]
	v_exp_f32_e32 v36, v36
	v_exp_f32_e32 v37, v37
	v_pk_mul_f32 v[20:21], v[6:7], v[34:35]
	v_pk_add_f32 v[6:7], v[170:171], v[24:25]
	v_pk_add_f32 v[30:31], v[170:171], v[30:31]
	v_pk_add_f32 v[24:25], v[36:37], 1.0 op_sel_hi:[1,0]
	v_pk_mul_f32 v[6:7], v[6:7], s[90:91] op_sel_hi:[1,0]
	v_rcp_f32_e32 v24, v24
	v_rcp_f32_e32 v25, v25
	v_exp_f32_e32 v34, v6
	v_exp_f32_e32 v35, v7
	v_pk_add_f32 v[36:37], v[168:169], v[42:43]
	v_pk_mul_f32 v[6:7], v[174:175], v[24:25]
	v_pk_mul_f32 v[36:37], v[36:37], s[90:91] op_sel_hi:[1,0]
	v_pk_add_f32 v[24:25], v[34:35], 1.0 op_sel_hi:[1,0]
	v_exp_f32_e32 v36, v36
	v_rcp_f32_e32 v24, v24
	v_rcp_f32_e32 v25, v25
	v_exp_f32_e32 v37, v37
	v_exp_f32_e32 v6, v6
	v_exp_f32_e32 v7, v7
	v_pk_mul_f32 v[8:9], v[8:9], v[24:25]
	v_pk_add_f32 v[24:25], v[170:171], v[26:27]
	v_pk_add_f32 v[26:27], v[36:37], 1.0 op_sel_hi:[1,0]
	v_pk_fma_f32 v[34:35], v[6:7], v[6:7], 1.0 op_sel_hi:[1,1,0] neg_lo:[1,0,0] neg_hi:[1,0,0]
	v_rcp_f32_e32 v26, v26
	v_rcp_f32_e32 v27, v27
	v_max_f32_e32 v34, 0, v34
	v_max_f32_e32 v35, 0, v35
	v_sqrt_f32_e32 v34, v34
	v_sqrt_f32_e32 v35, v35
	v_pk_mul_f32 v[24:25], v[24:25], s[90:91] op_sel_hi:[1,0]
	v_pk_mul_f32 v[26:27], v[174:175], v[26:27]
	v_exp_f32_e32 v24, v24
	v_exp_f32_e32 v25, v25
	v_exp_f32_e32 v40, v26
	v_exp_f32_e32 v41, v27
	v_pk_mul_f32 v[8:9], v[8:9], v[34:35]
	v_pk_add_f32 v[34:35], v[168:169], v[44:45]
	v_pk_add_f32 v[24:25], v[24:25], 1.0 op_sel_hi:[1,0]
	v_pk_mul_f32 v[34:35], v[34:35], s[90:91] op_sel_hi:[1,0]
	v_rcp_f32_e32 v24, v24
	v_rcp_f32_e32 v25, v25
; template <int DIR>
; __device__ __forceinline__ void lru_item(const Params& p, int item, int lane) {
;     ...
;         for (int e = 0; e < 16; e += 2) {
;             const f32x2 xa = (f32x2){Aa[e], Aa[e + 1]} + ba, xi = (f32x2){Ai[e], Ai[e + 1]} + bi, uv = (f32x2){Au[e], Au[e + 1]};
;             const f32x2 ta = xa * -1.4426950408889634f, ti = xi * -1.4426950408889634f;
;             f32x2 da, di; da.x = __builtin_amdgcn_exp2f(ta.x); da.y = __builtin_amdgcn_exp2f(ta.y); di.x = __builtin_amdgcn_exp2f(ti.x); di.y = __builtin_amdgcn_exp2f(ti.y);
;             da = da + 1.f; di = di + 1.f;
;             f32x2 ra, ri; ra.x = __builtin_amdgcn_rcpf(da.x); ra.y = __builtin_amdgcn_rcpf(da.y); ri.x = __builtin_amdgcn_rcpf(di.x); ri.y = __builtin_amdgcn_rcpf(di.y);
;             const f32x2 la = ra * (c8 * 1.4426950408889634f);
;             f32x2 a; a.x = __builtin_amdgcn_exp2f(la.x); a.y = __builtin_amdgcn_exp2f(la.y);
;             f32x2 om = 1.f - a * a; om.x = fmaxf(om.x, 0.f); om.y = fmaxf(om.y, 0.f);
;             f32x2 sq; sq.x = __builtin_amdgcn_sqrtf(om.x); sq.y = __builtin_amdgcn_sqrtf(om.y);
;             const f32x2 b = sq * (ri * uv);
;             const int k0 = DIR ? 15 - e : e, k1 = DIR ? 14 - e : e + 1;
;             av[k0] = a.x; bv[k0] = b.x; av[k1] = a.y; bv[k1] = b.y;
;         }
;         const int hh = DIR ? 1 - h : h;
;         float Ag[4], Bg[4];
; #pragma unroll
;         for (int q = 0; q < 4; q += 2) {
;             f32x2 A = (f32x2){av[4 * q], av[4 * q + 4]}, B = (f32x2){bv[4 * q], bv[4 * q + 4]};
; #pragma unroll
;             for (int k = 1; k < 4; ++k) { const f32x2 ak = (f32x2){av[4 * q + k], av[4 * q + 4 + k]}, bk = (f32x2){bv[4 * q + k], bv[4 * q + 4 + k]};
;                 A = A * ak; B = B * ak + bk; av[4 * q + k] = A.x; av[4 * q + 4 + k] = A.y; bv[4 * q + k] = B.x; bv[4 * q + 4 + k] = B.y; }
;             Ag[q] = A.x; Ag[q + 1] = A.y; Bg[q] = B.x; Bg[q + 1] = B.y;
;         }
;         float Ap[4], Bp[4];
; #pragma unroll
;         for (int q = 0; q < 4; ++q) { Ap[q] = lane_get(Ag[q], lane ^ 32); Bp[q] = lane_get(Bg[q], lane ^ 32); }
;         float st = hst, hs[4];
; #pragma unroll
;         for (int Gi = 0; Gi < 8; ++Gi) {
;             const int q = Gi >> 1; const bool own = (hh == (Gi & 1));
;             const float A = own ? Ag[q] : Ap[q], B = own ? Bg[q] : Bp[q];
;             if (own) hs[q] = st;
	v_exp_f32_e32 v34, v34
	v_exp_f32_e32 v35, v35
	v_pk_fma_f32 v[26:27], v[40:41], v[40:41], 1.0 op_sel_hi:[1,1,0] neg_lo:[1,0,0] neg_hi:[1,0,0]
	v_pk_mul_f32 v[10:11], v[10:11], v[24:25]
	v_max_f32_e32 v26, 0, v26
	v_max_f32_e32 v27, 0, v27
	v_sqrt_f32_e32 v26, v26
	v_sqrt_f32_e32 v27, v27
	v_pk_add_f32 v[24:25], v[34:35], 1.0 op_sel_hi:[1,0]
	v_exp_f32_e32 v16, v16
	v_rcp_f32_e32 v24, v24
	v_rcp_f32_e32 v25, v25
	v_pk_mul_f32 v[42:43], v[10:11], v[26:27]
	v_pk_add_f32 v[10:11], v[170:171], v[28:29]
	v_exp_f32_e32 v17, v17
	v_pk_mul_f32 v[10:11], v[10:11], s[90:91] op_sel_hi:[1,0]
	v_pk_mul_f32 v[30:31], v[30:31], s[90:91] op_sel_hi:[1,0]
	v_exp_f32_e32 v26, v10
	v_exp_f32_e32 v27, v11
	v_pk_mul_f32 v[10:11], v[174:175], v[24:25]
	v_exp_f32_e32 v30, v30
	v_exp_f32_e32 v10, v10
	v_exp_f32_e32 v11, v11
	v_pk_add_f32 v[24:25], v[26:27], 1.0 op_sel_hi:[1,0]
	v_exp_f32_e32 v31, v31
	v_pk_fma_f32 v[182:183], v[16:17], v[16:17], 1.0 op_sel_hi:[1,1,0] neg_lo:[1,0,0] neg_hi:[1,0,0]
	v_pk_fma_f32 v[26:27], v[10:11], v[10:11], 1.0 op_sel_hi:[1,1,0] neg_lo:[1,0,0] neg_hi:[1,0,0]
	v_max_f32_e32 v179, 0, v182
	v_max_f32_e32 v28, 0, v26
	v_max_f32_e32 v29, 0, v27
	v_pk_add_f32 v[26:27], v[168:169], v[46:47]
	v_max_f32_e32 v183, 0, v183
	v_pk_mul_f32 v[26:27], v[26:27], s[90:91] op_sel_hi:[1,0]
	v_sqrt_f32_e32 v182, v179
	v_exp_f32_e32 v26, v26
	v_exp_f32_e32 v27, v27
	v_sqrt_f32_e32 v183, v183
	v_rcp_f32_e32 v24, v24
	v_rcp_f32_e32 v25, v25
	v_pk_add_f32 v[26:27], v[26:27], 1.0 op_sel_hi:[1,0]
	v_sqrt_f32_e32 v28, v28
	v_rcp_f32_e32 v26, v26
	v_rcp_f32_e32 v27, v27
	v_sqrt_f32_e32 v29, v29
	v_pk_mul_f32 v[0:1], v[0:1], v[182:183]
	v_pk_mul_f32 v[12:13], v[12:13], v[24:25]
	v_pk_mul_f32 v[26:27], v[174:175], v[26:27]
	v_mov_b32_e32 v24, v0
	v_exp_f32_e32 v44, v26
	v_exp_f32_e32 v45, v27
	v_pk_add_f32 v[26:27], v[30:31], 1.0 op_sel_hi:[1,0]
	v_mov_b32_e32 v25, v4
	v_rcp_f32_e32 v26, v26
	v_pk_fma_f32 v[30:31], v[44:45], v[44:45], 1.0 op_sel_hi:[1,1,0] neg_lo:[1,0,0] neg_hi:[1,0,0]
	v_rcp_f32_e32 v27, v27
	v_max_f32_e32 v30, 0, v30
	v_max_f32_e32 v31, 0, v31
	v_sqrt_f32_e32 v30, v30
	v_sqrt_f32_e32 v31, v31
	v_pk_mul_f32 v[14:15], v[14:15], v[26:27]
	v_mov_b32_e32 v26, v17
	v_mov_b32_e32 v27, v3
	v_pk_mul_f32 v[46:47], v[14:15], v[30:31]
	v_mov_b32_e32 v14, v16
	v_mov_b32_e32 v15, v2
	v_mov_b32_e32 v30, v1
	v_mov_b32_e32 v31, v5
	v_pk_mul_f32 v[12:13], v[12:13], v[28:29]
	v_pk_mul_f32 v[28:29], v[14:15], v[26:27]
	v_pk_fma_f32 v[30:31], v[26:27], v[24:25], v[30:31]
	v_mov_b32_e32 v14, v18
	v_mov_b32_e32 v15, v22
	v_mov_b32_e32 v24, v32
	v_mov_b32_e32 v25, v20
	v_pk_mul_f32 v[34:35], v[14:15], v[28:29]
	v_pk_fma_f32 v[36:37], v[14:15], v[30:31], v[24:25]
	v_mov_b32_e32 v22, v19
	v_mov_b32_e32 v20, v33
	v_pk_mul_f32 v[32:33], v[22:23], v[34:35]
	v_pk_fma_f32 v[38:39], v[22:23], v[36:37], v[20:21]
	v_mov_b32_e32 v14, v6
	v_mov_b32_e32 v15, v10
	v_mov_b32_e32 v18, v8
	v_mov_b32_e32 v19, v12
	v_mov_b32_e32 v22, v7
	v_mov_b32_e32 v23, v11
	v_mov_b32_e32 v24, v9
	v_mov_b32_e32 v25, v13
	ds_bpermute_b32 v5, v180, v32
	ds_bpermute_b32 v9, v180, v38
	v_pk_mul_f32 v[20:21], v[14:15], v[22:23]
	v_pk_fma_f32 v[22:23], v[22:23], v[18:19], v[24:25]
	v_mov_b32_e32 v14, v40
	v_mov_b32_e32 v15, v44
	v_mov_b32_e32 v18, v42
	v_mov_b32_e32 v19, v46
	v_pk_mul_f32 v[24:25], v[14:15], v[20:21]
	v_pk_fma_f32 v[26:27], v[14:15], v[22:23], v[18:19]
	v_mov_b32_e32 v44, v41
	v_mov_b32_e32 v46, v43
	ds_bpermute_b32 v13, v180, v33
	ds_bpermute_b32 v17, v180, v39
	v_pk_mul_f32 v[14:15], v[44:45], v[24:25]
	v_pk_fma_f32 v[18:19], v[44:45], v[26:27], v[46:47]
	ds_bpermute_b32 v40, v180, v14
	ds_bpermute_b32 v41, v180, v18
	s_waitcnt lgkmcnt(0)
	v_cndmask_b32_e64 v11, v5, v32, s[2:3]
	v_cndmask_b32_e64 v7, v9, v38, s[2:3]
	ds_bpermute_b32 v1, v180, v15
	ds_bpermute_b32 v3, v180, v19
	v_fmac_f32_e32 v7, v178, v11
	v_cndmask_b32_e64 v5, v32, v5, s[2:3]
	v_cndmask_b32_e64 v9, v38, v9, s[2:3]
	v_fmac_f32_e32 v9, v5, v7
	v_cndmask_b32_e64 v5, v13, v33, s[2:3]
	v_cndmask_b32_e64 v11, v17, v39, s[2:3]
	v_fmac_f32_e32 v11, v5, v9
	v_cndmask_b32_e64 v5, v33, v13, s[2:3]
	v_cndmask_b32_e64 v13, v39, v17, s[2:3]
	v_fmac_f32_e32 v13, v5, v11
	v_cndmask_b32_e64 v5, v40, v14, s[2:3]
	v_cndmask_b32_e64 v17, v41, v18, s[2:3]
	v_fmac_f32_e32 v17, v5, v13
	v_cndmask_b32_e64 v5, v14, v40, s[2:3]
	v_cndmask_b32_e64 v40, v18, v41, s[2:3]
	v_fmac_f32_e32 v40, v5, v17
	s_waitcnt lgkmcnt(1)
	v_cndmask_b32_e64 v41, v1, v15, s[2:3]
	s_waitcnt lgkmcnt(0)
	v_cndmask_b32_e64 v5, v3, v19, s[2:3]
	s_cmp_lt_u32 s19, 8
	v_fmac_f32_e32 v5, v41, v40
	s_waitcnt vmcnt(0)
	s_cbranch_scc1 .LBB0_490
; __device__ __forceinline__ unsigned short f2bf(float f) { return (unsigned short)(cvt_pk_bf16(f, 0.f) & 0xffffu); }
; template <int DIR>
; __device__ __forceinline__ void lru_item(const Params& p, int item, int lane) {
;     ...
;         float st = hst, hs[4];
; #pragma unroll
;         for (int Gi = 0; Gi < 8; ++Gi) {
;             const int q = Gi >> 1; const bool own = (hh == (Gi & 1));
;             const float A = own ? Ag[q] : Ap[q], B = own ? Bg[q] : Bp[q];
;             if (own) hs[q] = st;
;             st = A * st + B;
;         }
;         hst = st;
;         if (!is_ctx) {
;             bf16_t* yr = yl + ((size_t)bl * 2048 + tile * 32) * 1024 + d;
; #pragma unroll
;             for (int e = 0; e < 16; ++e) { const int k = DIR ? 15 - e : e; const float hv = av[k] * hs[k >> 2] + bv[k];
;                 const int tok = (e & 3) + 8 * (e >> 2) + 4 * h; yr[(size_t)tok * 1024] = f2bf(hv); }
;         }
	v_cndmask_b32_e64 v7, v7, v178, s[2:3]
	v_cndmask_b32_e64 v13, v17, v13, s[2:3]
	v_fmac_f32_e32 v0, v16, v7
	v_lshl_add_u64 v[16:17], v[176:177], 0, s[10:11]
	s_mov_b32 s12, 0x17880000
	v_cndmask_b32_e64 v44, v5, v40, s[2:3]
	v_add_co_u32_e32 v40, vcc, s12, v16
	s_mov_b32 s12, 0x17881000
	s_nop 0
	v_addc_co_u32_e32 v41, vcc, 0, v17, vcc
	v_add_co_u32_e32 v42, vcc, s12, v16
	v_cvt_pk_bf16_f32 v0, v0, v193
	s_mov_b32 s12, 0x17884000
	s_nop 0
	v_addc_co_u32_e32 v43, vcc, 0, v17, vcc
	global_store_short v[42:43], v0, off offset:-4096
	v_fma_f32 v0, v28, v7, v30
	v_cvt_pk_bf16_f32 v0, v0, v193
	global_store_short v[40:41], v0, off offset:2048
	v_fma_f32 v0, v34, v7, v36
	v_cvt_pk_bf16_f32 v0, v0, v193
	v_add_co_u32_e32 v40, vcc, s12, v16
	global_store_short v[42:43], v0, off
	v_fma_f32 v0, v32, v7, v38
	v_addc_co_u32_e32 v41, vcc, 0, v17, vcc
	s_mov_b32 s12, 0x17885000
	v_cndmask_b32_e64 v9, v11, v9, s[2:3]
	v_cvt_pk_bf16_f32 v0, v0, v193
	global_store_short v[42:43], v0, off offset:2048
	v_add_co_u32_e32 v42, vcc, s12, v16
	v_fmac_f32_e32 v4, v2, v9
	v_cvt_pk_bf16_f32 v0, v4, v193
	s_nop 0
	v_addc_co_u32_e32 v43, vcc, 0, v17, vcc
	global_store_short v[42:43], v0, off offset:-4096
	v_fmac_f32_e32 v31, v29, v9
	v_cvt_pk_bf16_f32 v0, v31, v193
	s_mov_b32 s12, 0x17888000
	global_store_short v[40:41], v0, off offset:2048
	v_fmac_f32_e32 v37, v35, v9
	v_cvt_pk_bf16_f32 v0, v37, v193
	v_fmac_f32_e32 v8, v6, v13
	v_add_co_u32_e32 v6, vcc, s12, v16
	global_store_short v[42:43], v0, off
	v_fmac_f32_e32 v39, v33, v9
	v_cvt_pk_bf16_f32 v0, v39, v193
	v_addc_co_u32_e32 v7, vcc, 0, v17, vcc
	s_mov_b32 s12, 0x17889000
	global_store_short v[42:43], v0, off offset:2048
	v_cvt_pk_bf16_f32 v0, v8, v193
	v_add_co_u32_e32 v8, vcc, s12, v16
	v_fmac_f32_e32 v12, v10, v44
	s_nop 0
	v_addc_co_u32_e32 v9, vcc, 0, v17, vcc
	global_store_short v[8:9], v0, off offset:-4096
	v_fma_f32 v0, v20, v13, v22
	v_cvt_pk_bf16_f32 v0, v0, v193
	global_store_short v[6:7], v0, off offset:2048
	v_fma_f32 v0, v24, v13, v26
	v_cvt_pk_bf16_f32 v0, v0, v193
	global_store_short v[8:9], v0, off
	v_fma_f32 v0, v14, v13, v18
	v_cvt_pk_bf16_f32 v0, v0, v193
	v_add_co_u32_e32 v6, vcc, 0x1788c000, v16
	global_store_short v[8:9], v0, off offset:2048
	v_cvt_pk_bf16_f32 v0, v12, v193
	s_nop 0
	v_addc_co_u32_e32 v7, vcc, 0, v17, vcc
	global_store_short v[6:7], v0, off
	v_fmac_f32_e32 v23, v21, v44
	v_cvt_pk_bf16_f32 v0, v23, v193
	global_store_short v[6:7], v0, off offset:2048
	v_add_co_u32_e32 v6, vcc, 0x1788d000, v16
	v_fmac_f32_e32 v27, v25, v44
	v_cvt_pk_bf16_f32 v0, v27, v193
	s_nop 0
	v_addc_co_u32_e32 v7, vcc, 0, v17, vcc
	global_store_short v[6:7], v0, off
	v_fma_f32 v0, v15, v44, v19
	v_cvt_pk_bf16_f32 v0, v0, v193
	s_nop 1
	global_store_short v[6:7], v0, off offset:2048
	s_branch .LBB0_490

; __device__ __forceinline__ void phase_ln0(const Params& p, int g, int gw, int NGW, int lane) {
;     const float* mod = (const float*)(p.ws + OFF_MOD); bf16_t* h0 = (bf16_t*)(p.ws + OFF_H0);
;     f32x4 nx[4];
;     if (gw < RG) { const float* src = ln0_src(p, g, gw);
; #pragma unroll
;         for (int j = 0; j < 4; ++j) nx[j] = *(const f32x4*)(src + 4 * lane + 256 * j); }
;     for (int row = gw; row < RG; row += NGW) {
;         const int mrow = (row < CGR) ? 32 : g * BG + (row - CGR) / SEQ;
.LBB0_676:
	s_cmp_lg_u32 s79, 1
	s_mov_b64 s[0:1], -1
	s_cbranch_scc0 .LBB0_685
	s_cmp_gt_i32 s26, 0x8fff
	s_cbranch_scc1 .LBB0_684
	s_waitcnt lgkmcnt(0)
	s_add_i32 s6, s26, 0xfffff000
	s_ashr_i32 s27, s26, 31
	s_cmpk_lt_i32 s26, 0x1000
	s_cselect_b32 s2, 24, 27
	s_cselect_b32 s4, s61, s45
	s_cselect_b32 s5, s60, s44
	s_cselect_b32 s1, s27, 0
	s_cselect_b32 s0, s26, s6
	s_lshl_b64 s[2:3], s[38:39], s2
	s_add_u32 s2, s5, s2
	s_addc_u32 s3, s4, s3
	s_lshl_b64 s[0:1], s[0:1], 12
	s_add_u32 s0, s2, s0
	s_addc_u32 s1, s3, s1
	v_lshlrev_b32_e32 v0, 4, v244
	global_load_dwordx4 v[12:15], v0, s[0:1]
	global_load_dwordx4 v[8:11], v0, s[0:1] offset:1024
	global_load_dwordx4 v[4:7], v0, s[0:1] offset:2048
	s_nop 0
	global_load_dwordx4 v[0:3], v0, s[0:1] offset:3072
	s_lshl_b64 s[0:1], s[26:27], 11
	s_add_u32 s0, s94, s0
	v_lshlrev_b32_e32 v16, 2, v244
	v_lshlrev_b32_e32 v192, 3, v244
	s_addc_u32 s1, s95, s1
	v_or_b32_e32 v18, 0x100, v16
	v_or_b32_e32 v20, 0x200, v16
	v_or_b32_e32 v22, 0x300, v16
	v_lshl_add_u64 v[24:25], s[0:1], 0, v[192:193]
	s_mov_b64 s[0:1], 0x3100000
	v_xor_b32_e32 v34, 4, v16
	v_xor_b32_e32 v35, 8, v16
	v_xor_b32_e32 v36, 16, v16
	v_xor_b32_e32 v37, 32, v16
	v_xor_b32_e32 v38, 64, v16
	v_xor_b32_e32 v39, 0x80, v16
	v_lshl_add_u64 v[32:33], v[24:25], 0, s[0:1]
	v_lshlrev_b32_e32 v40, 2, v16
	v_lshlrev_b32_e32 v41, 2, v18
	v_lshlrev_b32_e32 v42, 2, v20
	v_lshlrev_b32_e32 v43, 2, v22
	s_waitcnt vmcnt(0)
	s_branch .LBB0_680
; __device__ __forceinline__ unsigned cvt_pk_bf16(float lo, float hi) { unsigned r; asm volatile("s_nop 0\n\tv_cvt_pk_bf16_f32 %0, %1, %2\n\ts_nop 1" : "=v"(r) : "v"(lo), "v"(hi)); return r; }
; __device__ __forceinline__ void phase_ln0(const Params& p, int g, int gw, int NGW, int lane) {
;     ...
;         f32x4 v[4]; float s = 0.f;
; #pragma unroll
;         for (int j = 0; j < 4; ++j) { v[j] = nx[j]; s += (v[j].x + v[j].y) + (v[j].z + v[j].w); }
;         if (row + NGW < RG) { const float* src = ln0_src(p, g, row + NGW);
; #pragma unroll
;             for (int j = 0; j < 4; ++j) nx[j] = *(const f32x4*)(src + 4 * lane + 256 * j); }
;         const float mean = wave_sum(s, lane) * (1.f / DM); float s2 = 0.f;
; #pragma unroll
;         for (int j = 0; j < 4; ++j) { v[j] = v[j] - mean; s2 += (v[j].x * v[j].x + v[j].y * v[j].y) + (v[j].z * v[j].z + v[j].w * v[j].w); }
;         const float rstd = __builtin_amdgcn_rsqf(wave_sum(s2, lane) * (1.f / DM) + 1e-6f);
; #pragma unroll
;         for (int j = 0; j < 4; ++j) { const int col = 4 * lane + 256 * j; const f32x4 a = *(const f32x4*)(sc + col), b = *(const f32x4*)(sh + col);
;             const f32x4 o = v[j] * rstd * (a + 1.f) + b; u32x2 w; w.x = cvt_pk_bf16(o.x, o.y); w.y = cvt_pk_bf16(o.z, o.w);
;             *(u32x2*)(h0 + (size_t)row * DM + col) = w; }
.LBB0_679:
	v_add_f32_e32 v44, v12, v13
	v_add_f32_e32 v45, v14, v15
	v_add_f32_e32 v44, v44, v45
	v_add_f32_e32 v45, v8, v9
	v_add_f32_e32 v46, v10, v11
	v_add_f32_e32 v44, 0, v44
	v_add_f32_e32 v45, v45, v46
	v_add_f32_e32 v44, v45, v44
	v_add_f32_e32 v45, v4, v5
	v_add_f32_e32 v46, v6, v7
	v_add_f32_e32 v45, v45, v46
	v_add_f32_e32 v44, v45, v44
	v_add_f32_e32 v45, v0, v1
	v_add_f32_e32 v46, v2, v3
	v_add_f32_e32 v45, v45, v46
	v_add_f32_e32 v44, v45, v44
	ds_bpermute_b32 v45, v34, v44
	s_lshl_b64 s[2:3], s[2:3], 2
	s_add_u32 s2, s94, s2
	s_addc_u32 s3, s95, s3
	s_add_u32 s4, s2, 0x1000
	s_waitcnt lgkmcnt(0)
	v_add_f32_e32 v44, v44, v45
	ds_bpermute_b32 v45, v35, v44
	s_addc_u32 s5, s3, 0
	s_and_b64 vcc, exec, s[0:1]
	v_readlane_b32 s0, v255, 2
	v_readlane_b32 s1, v255, 3
	s_waitcnt lgkmcnt(0)
	v_add_f32_e32 v44, v44, v45
	ds_bpermute_b32 v45, v36, v44
	s_waitcnt lgkmcnt(0)
	v_add_f32_e32 v44, v44, v45
	ds_bpermute_b32 v45, v37, v44
	s_waitcnt lgkmcnt(0)
	v_add_f32_e32 v44, v44, v45
	ds_bpermute_b32 v45, v38, v44
	s_waitcnt lgkmcnt(0)
	v_add_f32_e32 v52, v44, v45
	global_load_dwordx4 v[44:47], v40, s[4:5]
	global_load_dwordx4 v[48:51], v40, s[2:3]
	global_load_dwordx4 v[100:103], v41, s[4:5]
	global_load_dwordx4 v[104:107], v40, s[2:3] offset:1024
	global_load_dwordx4 v[108:111], v42, s[4:5]
	global_load_dwordx4 v[112:115], v40, s[2:3] offset:2048
	global_load_dwordx4 v[116:119], v43, s[4:5]
	global_load_dwordx4 v[120:123], v40, s[2:3] offset:3072
	ds_bpermute_b32 v53, v39, v52
	s_waitcnt lgkmcnt(0)
	v_add_f32_e32 v60, v52, v53
	v_fmac_f32_e32 v13, 0xba800000, v60
	v_fmac_f32_e32 v12, 0xba800000, v60
	v_fmac_f32_e32 v15, 0xba800000, v60
	v_fmac_f32_e32 v14, 0xba800000, v60
	v_pk_mul_f32 v[52:53], v[14:15], v[14:15]
	v_pk_mul_f32 v[54:55], v[12:13], v[12:13]
	v_fmac_f32_e32 v9, 0xba800000, v60
	v_pk_mov_b32 v[56:57], v[54:55], v[52:53] op_sel:[1,0]
	v_mov_b32_e32 v55, v53
	v_fmac_f32_e32 v8, 0xba800000, v60
	v_pk_add_f32 v[52:53], v[56:57], v[54:55]
	v_fmac_f32_e32 v11, 0xba800000, v60
	v_fmac_f32_e32 v10, 0xba800000, v60
	v_pk_add_f32 v[52:53], v[52:53], v[52:53] op_sel_hi:[0,1]
	v_pk_mul_f32 v[54:55], v[10:11], v[10:11]
	v_pk_mul_f32 v[56:57], v[8:9], v[8:9]
	v_fmac_f32_e32 v4, 0xba800000, v60
	v_pk_mov_b32 v[58:59], v[56:57], v[54:55] op_sel:[1,0]
	v_mov_b32_e32 v57, v55
	v_fmac_f32_e32 v5, 0xba800000, v60
	v_fmac_f32_e32 v6, 0xba800000, v60
	v_mul_f32_e32 v52, v4, v4
	v_pk_add_f32 v[54:55], v[58:59], v[56:57]
	v_fmac_f32_e32 v7, 0xba800000, v60
	v_pk_fma_f32 v[56:57], v[4:5], v[4:5], v[52:53] op_sel_hi:[1,1,0]
	v_mul_f32_e32 v52, v6, v6
	v_pk_add_f32 v[54:55], v[54:55], v[54:55] op_sel_hi:[0,1]
	v_pk_fma_f32 v[58:59], v[6:7], v[6:7], v[52:53] op_sel_hi:[1,1,0]
	v_fmac_f32_e32 v3, 0xba800000, v60
	v_fmac_f32_e32 v2, 0xba800000, v60
	v_fmac_f32_e32 v1, 0xba800000, v60
	v_fmac_f32_e32 v0, 0xba800000, v60
	v_mul_f32_e32 v56, v0, v0
	v_mul_f32_e32 v58, v1, v1
	v_mul_f32_e32 v52, v2, v2
	v_mul_f32_e32 v54, v3, v3
	v_pk_add_f32 v[56:57], v[56:57], v[58:59]
	v_pk_add_f32 v[52:53], v[52:53], v[54:55]
	s_waitcnt vmcnt(0)
	v_pk_add_f32 v[44:45], v[44:45], 1.0 op_sel_hi:[1,0]
	v_pk_add_f32 v[52:53], v[56:57], v[52:53]
	v_pk_add_f32 v[46:47], v[46:47], 1.0 op_sel_hi:[1,0]
	v_add_f32_e32 v52, v52, v53
	ds_bpermute_b32 v53, v34, v52
	s_waitcnt lgkmcnt(0)
	v_add_f32_e32 v52, v52, v53
	ds_bpermute_b32 v53, v35, v52
	s_waitcnt lgkmcnt(0)
	v_add_f32_e32 v52, v52, v53
	ds_bpermute_b32 v53, v36, v52
	s_waitcnt lgkmcnt(0)
	v_add_f32_e32 v52, v52, v53
	ds_bpermute_b32 v53, v37, v52
	s_waitcnt lgkmcnt(0)
	v_add_f32_e32 v52, v52, v53
	ds_bpermute_b32 v53, v38, v52
	s_waitcnt lgkmcnt(0)
	v_add_f32_e32 v52, v52, v53
	ds_bpermute_b32 v53, v39, v52
	s_waitcnt lgkmcnt(0)
	v_add_f32_e32 v52, v52, v53
	v_fmamk_f32 v52, v52, 0x3a800000, v238
	v_rsq_f32_e32 v52, v52
	s_nop 0
	v_pk_mul_f32 v[12:13], v[12:13], v[52:53] op_sel_hi:[1,0]
	v_pk_mul_f32 v[14:15], v[14:15], v[52:53] op_sel_hi:[1,0]
	v_pk_fma_f32 v[12:13], v[44:45], v[12:13], v[48:49]
	v_pk_fma_f32 v[14:15], v[46:47], v[14:15], v[50:51]
	v_cvt_pk_bf16_f32 v12, v12, v13
	v_pk_mul_f32 v[8:9], v[8:9], v[52:53] op_sel_hi:[1,0]
	v_cvt_pk_bf16_f32 v13, v14, v15
	global_store_dwordx2 v[32:33], v[12:13], off
	s_nop 0
	v_pk_mul_f32 v[10:11], v[10:11], v[52:53] op_sel_hi:[1,0]
	v_pk_mul_f32 v[4:5], v[4:5], v[52:53] op_sel_hi:[1,0]
	v_pk_mul_f32 v[6:7], v[6:7], v[52:53] op_sel_hi:[1,0]
	v_pk_mul_f32 v[54:55], v[0:1], v[52:53] op_sel_hi:[1,0]
	v_pk_mul_f32 v[52:53], v[2:3], v[52:53] op_sel_hi:[1,0]
	v_mov_b32_e32 v0, v28
	v_mov_b32_e32 v1, v29
	v_mov_b32_e32 v2, v30
	v_mov_b32_e32 v3, v31
	v_pk_add_f32 v[12:13], v[100:101], 1.0 op_sel_hi:[1,0]
	v_pk_add_f32 v[14:15], v[102:103], 1.0 op_sel_hi:[1,0]
	v_pk_fma_f32 v[8:9], v[12:13], v[8:9], v[104:105]
	v_pk_fma_f32 v[10:11], v[14:15], v[10:11], v[106:107]
	v_cvt_pk_bf16_f32 v8, v8, v9
	s_nop 0
	v_cvt_pk_bf16_f32 v9, v10, v11
	global_store_dwordx2 v[32:33], v[8:9], off offset:512
	s_nop 0
	v_pk_add_f32 v[8:9], v[108:109], 1.0 op_sel_hi:[1,0]
	v_pk_add_f32 v[10:11], v[110:111], 1.0 op_sel_hi:[1,0]
	v_pk_fma_f32 v[4:5], v[8:9], v[4:5], v[112:113]
	v_pk_fma_f32 v[6:7], v[10:11], v[6:7], v[114:115]
	v_cvt_pk_bf16_f32 v4, v4, v5
	v_mov_b32_e32 v14, v18
	v_cvt_pk_bf16_f32 v5, v6, v7
	global_store_dwordx2 v[32:33], v[4:5], off offset:1024
	v_mov_b32_e32 v15, v19
	v_mov_b32_e32 v12, v16
	v_mov_b32_e32 v13, v17
	v_mov_b32_e32 v8, v20
	v_mov_b32_e32 v9, v21
	v_mov_b32_e32 v10, v22
	v_mov_b32_e32 v11, v23
	v_mov_b32_e32 v4, v24
	v_mov_b32_e32 v5, v25
	v_mov_b32_e32 v6, v26
	v_mov_b32_e32 v7, v27
	v_pk_add_f32 v[18:19], v[116:117], 1.0 op_sel_hi:[1,0]
	v_pk_add_f32 v[16:17], v[118:119], 1.0 op_sel_hi:[1,0]
	v_pk_fma_f32 v[18:19], v[18:19], v[54:55], v[120:121]
	v_pk_fma_f32 v[16:17], v[16:17], v[52:53], v[122:123]
	v_cvt_pk_bf16_f32 v18, v18, v19
	s_nop 0
	v_cvt_pk_bf16_f32 v19, v16, v17
	global_store_dwordx2 v[32:33], v[18:19], off offset:1536
	v_lshl_add_u64 v[32:33], v[32:33], 0, s[0:1]
	s_cbranch_vccnz .LBB0_684

; __device__ __forceinline__ const float* ln0_src(const Params& p, int g, int row) {
;     return (row < CGR) ? p.ctx + ((size_t)g * CGR + row) * DM : p.x + ((size_t)g * TG + (row - CGR)) * DM;
; }
; __device__ __forceinline__ void phase_ln0(const Params& p, int g, int gw, int NGW, int lane) {
;     ...
;     for (int row = gw; row < RG; row += NGW) {
;         const int mrow = (row < CGR) ? 32 : g * BG + (row - CGR) / SEQ;
;         const float* sh = mod + (size_t)mrow * MODW; const float* sc = sh + DM;
;         f32x4 v[4]; float s = 0.f;
; #pragma unroll
;         for (int j = 0; j < 4; ++j) { v[j] = nx[j]; s += (v[j].x + v[j].y) + (v[j].z + v[j].w); }
;         if (row + NGW < RG) { const float* src = ln0_src(p, g, row + NGW);
; #pragma unroll
;             for (int j = 0; j < 4; ++j) nx[j] = *(const f32x4*)(src + 4 * lane + 256 * j); }
.LBB0_682:
	v_readlane_b32 s0, v255, 12
	s_add_i32 s6, s0, s6
	s_add_i32 s4, s6, 0x1000
	v_readlane_b32 s1, v255, 13
	s_cmp_gt_i32 s4, 0x8fff
	s_cselect_b64 s[0:1], -1, 0
	s_and_b64 vcc, exec, s[0:1]
	v_mov_b32_e32 v16, v12
	v_mov_b32_e32 v17, v13
	v_mov_b32_e32 v18, v14
	v_mov_b32_e32 v19, v15
	v_mov_b32_e32 v20, v8
	v_mov_b32_e32 v21, v9
	v_mov_b32_e32 v22, v10
	v_mov_b32_e32 v23, v11
	v_mov_b32_e32 v24, v4
	v_mov_b32_e32 v25, v5
	v_mov_b32_e32 v26, v6
	v_mov_b32_e32 v27, v7
	v_mov_b32_e32 v28, v0
	v_mov_b32_e32 v29, v1
	v_mov_b32_e32 v30, v2
	v_mov_b32_e32 v31, v3
	s_cbranch_vccnz .LBB0_679
	s_ashr_i32 s5, s4, 31
	s_cmpk_lt_i32 s4, 0x1000
	s_cselect_b32 s8, 24, 27
	s_cselect_b32 s7, s61, s45
	s_cselect_b32 s10, s60, s44
	s_cselect_b32 s5, s5, 0
	s_cselect_b32 s4, s4, s6
	s_lshl_b64 s[8:9], s[38:39], s8
	s_add_u32 s8, s10, s8
	s_addc_u32 s7, s7, s9
	s_lshl_b64 s[4:5], s[4:5], 12
	s_add_u32 s4, s8, s4
	s_addc_u32 s5, s7, s5
	global_load_dwordx4 v[16:19], v40, s[4:5]
	global_load_dwordx4 v[20:23], v40, s[4:5] offset:1024
	global_load_dwordx4 v[24:27], v40, s[4:5] offset:2048
	global_load_dwordx4 v[28:31], v40, s[4:5] offset:3072
	s_branch .LBB0_679
